# all plain skinny (sample-row) GEMM blocks re-pipelined: loads hoisted into a register ring with counted vmcnt
# baseline (speedup 1.0000x reference)
;     ...
;     for (int item = bx; item < nct * nrh * (8 / RB); item += G) {
;         const int ct = item % nct, rs = item / nct, row0 = rs * RB * 16, rh = row0 >> 7, rin = row0 & 127;
;         f32x4 acc[RB];
; #pragma unroll
;         for (int rb = 0; rb < RB; ++rb) acc[rb] = (f32x4){0.f, 0.f, 0.f, 0.f};
;         const bf16_t* bp = Wt + (size_t)(ct * 16 + fr) * ldb + wave * kw + fq * 8;
;         const bf16_t* ap = A + (size_t)(row0 + fr) * lda + wave * kw + fq * 8;
;         bf16x8 b0 = *(const bf16x8*)(bp), b1 = *(const bf16x8*)(bp + 32), a0[RB], a1[RB];
; #pragma unroll
;         for (int rb = 0; rb < RB; ++rb) { a0[rb] = *(const bf16x8*)(ap + (size_t)rb * 16 * lda); a1[rb] = *(const bf16x8*)(ap + (size_t)rb * 16 * lda + 32); }
;         for (int k = 0; k < kw; k += 64) {
;             bf16x8 nb0 = b0, nb1 = b1, na0[RB], na1[RB];
; #pragma unroll
;             for (int rb = 0; rb < RB; ++rb) { na0[rb] = a0[rb]; na1[rb] = a1[rb]; }
;             if (k + 64 < kw) {
;                 nb0 = *(const bf16x8*)(bp + k + 64); nb1 = *(const bf16x8*)(bp + k + 96);
; #pragma unroll
;                 for (int rb = 0; rb < RB; ++rb) { na0[rb] = *(const bf16x8*)(ap + (size_t)rb * 16 * lda + k + 64); na1[rb] = *(const bf16x8*)(ap + (size_t)rb * 16 * lda + k + 96); }
;             }
; #pragma unroll
;             for (int rb = 0; rb < RB; ++rb) acc[rb] = __builtin_amdgcn_mfma_f32_16x16x32_bf16(a0[rb], b0, acc[rb], 0, 0, 0);
; #pragma unroll
;             for (int rb = 0; rb < RB; ++rb) acc[rb] = __builtin_amdgcn_mfma_f32_16x16x32_bf16(a1[rb], b1, acc[rb], 0, 0, 0);
;             b0 = nb0; b1 = nb1;
; #pragma unroll
;             for (int rb = 0; rb < RB; ++rb) { a0[rb] = na0[rb]; a1[rb] = na1[rb]; }
;         }
.LBB0_118:
	s_ashr_i32 s4, s30, 31
	s_lshr_b32 s4, s4, 24
	s_add_i32 s4, s30, s4
	s_ashr_i32 s4, s4, 8
	s_lshl_b32 s31, s4, 7
	v_or_b32_e32 v20, s31, v8
	v_ashrrev_i32_e32 v21, 31, v20
	s_lshl_b32 s33, s4, 12
	v_lshlrev_b64 v[20:21], 12, v[20:21]
	s_sub_i32 s4, s29, s33
	v_lshl_add_u64 v[96:97], v[4:5], 0, v[20:21]
	v_add_u32_e32 v24, s4, v8
	v_add_co_u32_e64 v100, s[4:5], s19, v96
	s_nop 1
	v_addc_co_u32_e64 v101, s[4:5], 0, v97, s[4:5]
	v_add_co_u32_e64 v102, s[4:5], s20, v96
	v_ashrrev_i32_e32 v25, 31, v24
	s_nop 0
	v_addc_co_u32_e64 v103, s[4:5], 0, v97, s[4:5]
	v_add_co_u32_e64 v104, s[4:5], s21, v96
	v_lshlrev_b64 v[24:25], 12, v[24:25]
	s_nop 0
	v_addc_co_u32_e64 v105, s[4:5], 0, v97, s[4:5]
	v_add_co_u32_e64 v106, s[4:5], s22, v96
	v_lshl_add_u64 v[98:99], v[2:3], 0, v[24:25]
	s_nop 0
	v_addc_co_u32_e64 v107, s[4:5], 0, v97, s[4:5]
	v_add_co_u32_e64 v108, s[4:5], s23, v96
	s_nop 0
	s_nop 1
	v_addc_co_u32_e64 v109, s[4:5], 0, v97, s[4:5]
	v_add_co_u32_e64 v110, s[4:5], s27, v96
	s_nop 0
	s_nop 1
	v_addc_co_u32_e64 v111, s[4:5], 0, v97, s[4:5]
	v_add_co_u32_e64 v112, s[4:5], s28, v96
	s_nop 0
	s_nop 1
	v_addc_co_u32_e64 v113, s[4:5], 0, v97, s[4:5]
	global_load_dwordx4 v[58:61], v[96:97], off
	global_load_dwordx4 v[62:65], v[100:101], off
	global_load_dwordx4 v[66:69], v[102:103], off
	global_load_dwordx4 v[70:73], v[98:99], off
	global_load_dwordx4 v[74:77], v[104:105], off
	global_load_dwordx4 v[78:81], v[106:107], off
	global_load_dwordx4 v[82:85], v[108:109], off
	global_load_dwordx4 v[86:89], v[110:111], off
	global_load_dwordx4 v[90:93], v[112:113], off
	global_load_dwordx4 v[196:199], v[96:97], off offset:64
	global_load_dwordx4 v[200:203], v[98:99], off offset:64
	global_load_dwordx4 v[208:211], v[100:101], off offset:64
	global_load_dwordx4 v[212:215], v[102:103], off offset:64
	global_load_dwordx4 v[216:219], v[104:105], off offset:64
	global_load_dwordx4 v[220:223], v[106:107], off offset:64
	global_load_dwordx4 v[224:227], v[108:109], off offset:64
	global_load_dwordx4 v[228:231], v[110:111], off offset:64
	global_load_dwordx4 v[232:235], v[112:113], off offset:64
	global_load_dwordx4 v[236:239], v[96:97], off offset:128
	global_load_dwordx4 v[240:243], v[98:99], off offset:128
	global_load_dwordx4 v[244:247], v[100:101], off offset:128
	global_load_dwordx4 v[248:251], v[102:103], off offset:128
	s_waitcnt vmcnt(18)
	v_mfma_f32_16x16x32_bf16 v[26:29], v[58:61], v[70:73], 0
	global_load_dwordx4 v[58:61], v[104:105], off offset:128
	v_mfma_f32_16x16x32_bf16 v[30:33], v[62:65], v[70:73], 0
	global_load_dwordx4 v[62:65], v[106:107], off offset:128
	v_mfma_f32_16x16x32_bf16 v[34:37], v[66:69], v[70:73], 0
	global_load_dwordx4 v[66:69], v[108:109], off offset:128
	s_waitcnt vmcnt(20)
	v_mfma_f32_16x16x32_bf16 v[38:41], v[74:77], v[70:73], 0
	global_load_dwordx4 v[74:77], v[110:111], off offset:128
	s_waitcnt vmcnt(20)
	v_mfma_f32_16x16x32_bf16 v[42:45], v[78:81], v[70:73], 0
	global_load_dwordx4 v[78:81], v[112:113], off offset:128
	s_waitcnt vmcnt(20)
	v_mfma_f32_16x16x32_bf16 v[46:49], v[82:85], v[70:73], 0
	global_load_dwordx4 v[82:85], v[96:97], off offset:192
	s_waitcnt vmcnt(20)
	v_mfma_f32_16x16x32_bf16 v[50:53], v[86:89], v[70:73], 0
	global_load_dwordx4 v[86:89], v[98:99], off offset:192
	s_waitcnt vmcnt(20)
	v_mfma_f32_16x16x32_bf16 v[54:57], v[90:93], v[70:73], 0
	global_load_dwordx4 v[90:93], v[100:101], off offset:192
	global_load_dwordx4 v[70:73], v[102:103], off offset:192
	s_waitcnt vmcnt(20)
	v_mfma_f32_16x16x32_bf16 v[26:29], v[196:199], v[200:203], v[26:29]
	global_load_dwordx4 v[196:199], v[104:105], off offset:192
	s_waitcnt vmcnt(20)
	v_mfma_f32_16x16x32_bf16 v[30:33], v[208:211], v[200:203], v[30:33]
	global_load_dwordx4 v[208:211], v[106:107], off offset:192
	s_waitcnt vmcnt(20)
	v_mfma_f32_16x16x32_bf16 v[34:37], v[212:215], v[200:203], v[34:37]
	global_load_dwordx4 v[212:215], v[108:109], off offset:192
	s_waitcnt vmcnt(20)
	v_mfma_f32_16x16x32_bf16 v[38:41], v[216:219], v[200:203], v[38:41]
	global_load_dwordx4 v[216:219], v[110:111], off offset:192
	s_waitcnt vmcnt(20)
	v_mfma_f32_16x16x32_bf16 v[42:45], v[220:223], v[200:203], v[42:45]
	global_load_dwordx4 v[220:223], v[112:113], off offset:192
	s_waitcnt vmcnt(20)
	v_mfma_f32_16x16x32_bf16 v[46:49], v[224:227], v[200:203], v[46:49]
	global_load_dwordx4 v[224:227], v[96:97], off offset:256
	s_waitcnt vmcnt(20)
	v_mfma_f32_16x16x32_bf16 v[50:53], v[228:231], v[200:203], v[50:53]
	global_load_dwordx4 v[228:231], v[98:99], off offset:256
	s_waitcnt vmcnt(20)
	v_mfma_f32_16x16x32_bf16 v[54:57], v[232:235], v[200:203], v[54:57]
	global_load_dwordx4 v[232:235], v[100:101], off offset:256
	global_load_dwordx4 v[200:203], v[102:103], off offset:256
	s_waitcnt vmcnt(20)
	v_mfma_f32_16x16x32_bf16 v[26:29], v[236:239], v[240:243], v[26:29]
	global_load_dwordx4 v[236:239], v[104:105], off offset:256
	s_waitcnt vmcnt(20)
	v_mfma_f32_16x16x32_bf16 v[30:33], v[244:247], v[240:243], v[30:33]
	global_load_dwordx4 v[244:247], v[106:107], off offset:256
	s_waitcnt vmcnt(20)
	v_mfma_f32_16x16x32_bf16 v[34:37], v[248:251], v[240:243], v[34:37]
	global_load_dwordx4 v[248:251], v[108:109], off offset:256
	s_waitcnt vmcnt(20)
	v_mfma_f32_16x16x32_bf16 v[38:41], v[58:61], v[240:243], v[38:41]
	global_load_dwordx4 v[58:61], v[110:111], off offset:256
	s_waitcnt vmcnt(20)
	v_mfma_f32_16x16x32_bf16 v[42:45], v[62:65], v[240:243], v[42:45]
	global_load_dwordx4 v[62:65], v[112:113], off offset:256
	s_waitcnt vmcnt(20)
	v_mfma_f32_16x16x32_bf16 v[46:49], v[66:69], v[240:243], v[46:49]
	global_load_dwordx4 v[66:69], v[96:97], off offset:320
	s_waitcnt vmcnt(20)
;     ...
;         for (int k = 0; k < kw; k += 64) {
;             bf16x8 nb0 = b0, nb1 = b1, na0[RB], na1[RB];
; #pragma unroll
;             for (int rb = 0; rb < RB; ++rb) { na0[rb] = a0[rb]; na1[rb] = a1[rb]; }
;             if (k + 64 < kw) {
;                 nb0 = *(const bf16x8*)(bp + k + 64); nb1 = *(const bf16x8*)(bp + k + 96);
; #pragma unroll
;                 for (int rb = 0; rb < RB; ++rb) { na0[rb] = *(const bf16x8*)(ap + (size_t)rb * 16 * lda + k + 64); na1[rb] = *(const bf16x8*)(ap + (size_t)rb * 16 * lda + k + 96); }
;             }
; #pragma unroll
;             for (int rb = 0; rb < RB; ++rb) acc[rb] = __builtin_amdgcn_mfma_f32_16x16x32_bf16(a0[rb], b0, acc[rb], 0, 0, 0);
; #pragma unroll
;             for (int rb = 0; rb < RB; ++rb) acc[rb] = __builtin_amdgcn_mfma_f32_16x16x32_bf16(a1[rb], b1, acc[rb], 0, 0, 0);
;             b0 = nb0; b1 = nb1;
; #pragma unroll
;             for (int rb = 0; rb < RB; ++rb) { a0[rb] = na0[rb]; a1[rb] = na1[rb]; }
;         }
; #pragma unroll
;         for (int rb = 0; rb < RB; ++rb)
; #pragma unroll
;             for (int j = 0; j < 4; ++j) red[(wave * (RB * 16) + rb * 16 + 4 * fq + j) * 16 + fr] = acc[rb][j];
;         __syncthreads();
	v_mfma_f32_16x16x32_bf16 v[50:53], v[74:77], v[240:243], v[50:53]
	global_load_dwordx4 v[74:77], v[98:99], off offset:320
	s_waitcnt vmcnt(20)
	v_mfma_f32_16x16x32_bf16 v[54:57], v[78:81], v[240:243], v[54:57]
	global_load_dwordx4 v[78:81], v[100:101], off offset:320
	global_load_dwordx4 v[240:243], v[102:103], off offset:320
	s_waitcnt vmcnt(20)
	v_mfma_f32_16x16x32_bf16 v[26:29], v[82:85], v[86:89], v[26:29]
	global_load_dwordx4 v[82:85], v[104:105], off offset:320
	s_waitcnt vmcnt(20)
	v_mfma_f32_16x16x32_bf16 v[30:33], v[90:93], v[86:89], v[30:33]
	global_load_dwordx4 v[90:93], v[106:107], off offset:320
	s_waitcnt vmcnt(20)
	v_mfma_f32_16x16x32_bf16 v[34:37], v[70:73], v[86:89], v[34:37]
	global_load_dwordx4 v[70:73], v[108:109], off offset:320
	s_waitcnt vmcnt(20)
	v_mfma_f32_16x16x32_bf16 v[38:41], v[196:199], v[86:89], v[38:41]
	global_load_dwordx4 v[196:199], v[110:111], off offset:320
	s_waitcnt vmcnt(20)
	v_mfma_f32_16x16x32_bf16 v[42:45], v[208:211], v[86:89], v[42:45]
	global_load_dwordx4 v[208:211], v[112:113], off offset:320
	s_waitcnt vmcnt(20)
	v_mfma_f32_16x16x32_bf16 v[46:49], v[212:215], v[86:89], v[46:49]
	global_load_dwordx4 v[212:215], v[96:97], off offset:384
	s_waitcnt vmcnt(20)
	v_mfma_f32_16x16x32_bf16 v[50:53], v[216:219], v[86:89], v[50:53]
	global_load_dwordx4 v[216:219], v[98:99], off offset:384
	s_waitcnt vmcnt(20)
	v_mfma_f32_16x16x32_bf16 v[54:57], v[220:223], v[86:89], v[54:57]
	global_load_dwordx4 v[220:223], v[100:101], off offset:384
	global_load_dwordx4 v[86:89], v[102:103], off offset:384
	s_waitcnt vmcnt(20)
	v_mfma_f32_16x16x32_bf16 v[26:29], v[224:227], v[228:231], v[26:29]
	global_load_dwordx4 v[224:227], v[104:105], off offset:384
	s_waitcnt vmcnt(20)
	v_mfma_f32_16x16x32_bf16 v[30:33], v[232:235], v[228:231], v[30:33]
	global_load_dwordx4 v[232:235], v[106:107], off offset:384
	s_waitcnt vmcnt(20)
	v_mfma_f32_16x16x32_bf16 v[34:37], v[200:203], v[228:231], v[34:37]
	global_load_dwordx4 v[200:203], v[108:109], off offset:384
	s_waitcnt vmcnt(20)
	v_mfma_f32_16x16x32_bf16 v[38:41], v[236:239], v[228:231], v[38:41]
	global_load_dwordx4 v[236:239], v[110:111], off offset:384
	s_waitcnt vmcnt(20)
	v_mfma_f32_16x16x32_bf16 v[42:45], v[244:247], v[228:231], v[42:45]
	global_load_dwordx4 v[244:247], v[112:113], off offset:384
	s_waitcnt vmcnt(20)
	v_mfma_f32_16x16x32_bf16 v[46:49], v[248:251], v[228:231], v[46:49]
	global_load_dwordx4 v[248:251], v[96:97], off offset:448
	s_waitcnt vmcnt(20)
	v_mfma_f32_16x16x32_bf16 v[50:53], v[58:61], v[228:231], v[50:53]
	global_load_dwordx4 v[58:61], v[98:99], off offset:448
	s_waitcnt vmcnt(20)
	v_mfma_f32_16x16x32_bf16 v[54:57], v[62:65], v[228:231], v[54:57]
	global_load_dwordx4 v[62:65], v[100:101], off offset:448
	global_load_dwordx4 v[228:231], v[102:103], off offset:448
	s_waitcnt vmcnt(20)
	v_mfma_f32_16x16x32_bf16 v[26:29], v[66:69], v[74:77], v[26:29]
	global_load_dwordx4 v[66:69], v[104:105], off offset:448
	s_waitcnt vmcnt(20)
	v_mfma_f32_16x16x32_bf16 v[30:33], v[78:81], v[74:77], v[30:33]
	global_load_dwordx4 v[78:81], v[106:107], off offset:448
	s_waitcnt vmcnt(20)
	v_mfma_f32_16x16x32_bf16 v[34:37], v[240:243], v[74:77], v[34:37]
	global_load_dwordx4 v[240:243], v[108:109], off offset:448
	s_waitcnt vmcnt(20)
	v_mfma_f32_16x16x32_bf16 v[38:41], v[82:85], v[74:77], v[38:41]
	global_load_dwordx4 v[82:85], v[110:111], off offset:448
	s_waitcnt vmcnt(20)
	v_mfma_f32_16x16x32_bf16 v[42:45], v[90:93], v[74:77], v[42:45]
	global_load_dwordx4 v[90:93], v[112:113], off offset:448
	s_waitcnt vmcnt(20)
	v_mfma_f32_16x16x32_bf16 v[46:49], v[70:73], v[74:77], v[46:49]
	s_waitcnt vmcnt(19)
	v_mfma_f32_16x16x32_bf16 v[50:53], v[196:199], v[74:77], v[50:53]
	s_waitcnt vmcnt(18)
	v_mfma_f32_16x16x32_bf16 v[54:57], v[208:211], v[74:77], v[54:57]
	s_waitcnt vmcnt(16)
	v_mfma_f32_16x16x32_bf16 v[26:29], v[212:215], v[216:219], v[26:29]
	s_waitcnt vmcnt(15)
	v_mfma_f32_16x16x32_bf16 v[30:33], v[220:223], v[216:219], v[30:33]
	s_waitcnt vmcnt(14)
	v_mfma_f32_16x16x32_bf16 v[34:37], v[86:89], v[216:219], v[34:37]
	s_waitcnt vmcnt(13)
	v_mfma_f32_16x16x32_bf16 v[38:41], v[224:227], v[216:219], v[38:41]
	s_waitcnt vmcnt(12)
	v_mfma_f32_16x16x32_bf16 v[42:45], v[232:235], v[216:219], v[42:45]
	s_waitcnt vmcnt(11)
	v_mfma_f32_16x16x32_bf16 v[46:49], v[200:203], v[216:219], v[46:49]
	s_waitcnt vmcnt(10)
	v_mfma_f32_16x16x32_bf16 v[50:53], v[236:239], v[216:219], v[50:53]
	s_waitcnt vmcnt(7)
	v_mfma_f32_16x16x32_bf16 v[26:29], v[248:251], v[58:61], v[26:29]
	s_waitcnt vmcnt(6)
	v_mfma_f32_16x16x32_bf16 v[30:33], v[62:65], v[58:61], v[30:33]
	s_waitcnt vmcnt(5)
	v_mfma_f32_16x16x32_bf16 v[34:37], v[228:231], v[58:61], v[34:37]
	s_waitcnt vmcnt(4)
	v_mfma_f32_16x16x32_bf16 v[38:41], v[66:69], v[58:61], v[38:41]
	s_waitcnt vmcnt(3)
	v_mfma_f32_16x16x32_bf16 v[42:45], v[78:81], v[58:61], v[42:45]
	s_waitcnt vmcnt(2)
	v_mfma_f32_16x16x32_bf16 v[46:49], v[240:243], v[58:61], v[46:49]
	v_mfma_f32_16x16x32_bf16 v[54:57], v[244:247], v[216:219], v[54:57]
	s_waitcnt vmcnt(1)
	v_mfma_f32_16x16x32_bf16 v[50:53], v[82:85], v[58:61], v[50:53]
	s_waitcnt vmcnt(0)
	v_mfma_f32_16x16x32_bf16 v[54:57], v[90:93], v[58:61], v[54:57]
	s_nop 7
	s_nop 1
	ds_write2_b32 v1, v26, v27 offset1:16
	ds_write2_b32 v1, v28, v29 offset0:32 offset1:48
	ds_write2_b32 v13, v30, v31 offset1:16
	ds_write2_b32 v13, v32, v33 offset0:32 offset1:48
	ds_write2_b32 v14, v34, v35 offset1:16
	ds_write2_b32 v14, v36, v37 offset0:32 offset1:48
	ds_write2_b32 v15, v38, v39 offset1:16
	ds_write2_b32 v15, v40, v41 offset0:32 offset1:48
	ds_write2_b32 v16, v42, v43 offset1:16
	ds_write2_b32 v16, v44, v45 offset0:32 offset1:48
	ds_write2_b32 v17, v46, v47 offset1:16
	ds_write2_b32 v17, v48, v49 offset0:32 offset1:48
	ds_write2_b32 v18, v50, v51 offset1:16
	ds_write2_b32 v18, v52, v53 offset0:32 offset1:48
	ds_write2_b32 v19, v54, v55 offset1:16
	ds_write2_b32 v19, v56, v57 offset0:32 offset1:48
	s_waitcnt lgkmcnt(0)
	s_barrier
; #define LAS __attribute__((address_space(3)))
;     ...
;         if (tid < RB * 64) { const int e = tid * 4, row = e >> 4, col = e & 15;
;             f32x4 v = *(const LAS f32x4*)(red + row * 16 + col);
; #pragma unroll
;             for (int w = 1; w < 8; ++w) v += *(const LAS f32x4*)(red + (w * (RB * 16) + row) * 16 + col);
;             E(rin + row, rh, ct * 16 + col, v); }
	s_and_saveexec_b64 s[4:5], vcc
	s_cbranch_execz .LBB0_117
	ds_read_b128 v[20:23], v10
	ds_read_b128 v[24:27], v10 offset:8192
	ds_read_b128 v[28:31], v10 offset:16384
	ds_read_b128 v[32:35], v10 offset:24576
	s_sub_i32 s16, 0, s33
	s_add_i32 s16, s16, s29
	s_waitcnt lgkmcnt(2)
	v_pk_add_f32 v[22:23], v[22:23], v[26:27]
	v_pk_add_f32 v[24:25], v[20:21], v[24:25]
	s_waitcnt lgkmcnt(1)
	v_pk_add_f32 v[26:27], v[22:23], v[30:31]
	ds_read_b128 v[20:23], v10 offset:32768
	v_pk_add_f32 v[24:25], v[24:25], v[28:29]
	s_waitcnt lgkmcnt(1)
	v_pk_add_f32 v[28:29], v[26:27], v[34:35]
	v_pk_add_f32 v[32:33], v[24:25], v[32:33]
	ds_read_b128 v[24:27], v10 offset:40960
	s_waitcnt lgkmcnt(1)
	v_pk_add_f32 v[34:35], v[28:29], v[22:23]
	ds_read_b128 v[28:31], v10 offset:49152
	v_pk_add_f32 v[32:33], v[32:33], v[20:21]
	ds_read_b128 v[20:23], v10 offset:57344
	s_waitcnt lgkmcnt(2)
	v_pk_add_f32 v[26:27], v[34:35], v[26:27]
	v_pk_add_f32 v[24:25], v[32:33], v[24:25]
	s_waitcnt lgkmcnt(1)
	v_pk_add_f32 v[26:27], v[26:27], v[30:31]
	v_pk_add_f32 v[24:25], v[24:25], v[28:29]
	s_waitcnt lgkmcnt(0)
	v_pk_add_f32 v[22:23], v[26:27], v[22:23]
	v_pk_add_f32 v[20:21], v[24:25], v[20:21]
	v_add_u32_e32 v24, s16, v7
	v_cvt_pk_bf16_f32 v20, v20, v21
	v_cvt_pk_bf16_f32 v21, v22, v23
	v_or_b32_e32 v22, s31, v6
	v_ashrrev_i32_e32 v23, 31, v22
	v_lshlrev_b64 v[22:23], 13, v[22:23]
	v_lshl_add_u64 v[22:23], s[6:7], 0, v[22:23]
	v_ashrrev_i32_e32 v25, 31, v24
	v_lshl_add_u64 v[22:23], v[24:25], 1, v[22:23]
	global_store_dwordx2 v[22:23], v[20:21], off
	s_branch .LBB0_117

;     ...
;     for (int item = bx; item < nct * nrh * (8 / RB); item += G) {
;         const int ct = item % nct, rs = item / nct, row0 = rs * RB * 16, rh = row0 >> 7, rin = row0 & 127;
;         f32x4 acc[RB];
; #pragma unroll
;         for (int rb = 0; rb < RB; ++rb) acc[rb] = (f32x4){0.f, 0.f, 0.f, 0.f};
;         const bf16_t* bp = Wt + (size_t)(ct * 16 + fr) * ldb + wave * kw + fq * 8;
;         const bf16_t* ap = A + (size_t)(row0 + fr) * lda + wave * kw + fq * 8;
;         bf16x8 b0 = *(const bf16x8*)(bp), b1 = *(const bf16x8*)(bp + 32), a0[RB], a1[RB];
; #pragma unroll
;         for (int rb = 0; rb < RB; ++rb) { a0[rb] = *(const bf16x8*)(ap + (size_t)rb * 16 * lda); a1[rb] = *(const bf16x8*)(ap + (size_t)rb * 16 * lda + 32); }
;         for (int k = 0; k < kw; k += 64) {
;             bf16x8 nb0 = b0, nb1 = b1, na0[RB], na1[RB];
; #pragma unroll
;             for (int rb = 0; rb < RB; ++rb) { na0[rb] = a0[rb]; na1[rb] = a1[rb]; }
;             if (k + 64 < kw) {
;                 nb0 = *(const bf16x8*)(bp + k + 64); nb1 = *(const bf16x8*)(bp + k + 96);
; #pragma unroll
;                 for (int rb = 0; rb < RB; ++rb) { na0[rb] = *(const bf16x8*)(ap + (size_t)rb * 16 * lda + k + 64); na1[rb] = *(const bf16x8*)(ap + (size_t)rb * 16 * lda + k + 96); }
;             }
; #pragma unroll
;             for (int rb = 0; rb < RB; ++rb) acc[rb] = __builtin_amdgcn_mfma_f32_16x16x32_bf16(a0[rb], b0, acc[rb], 0, 0, 0);
; #pragma unroll
;             for (int rb = 0; rb < RB; ++rb) acc[rb] = __builtin_amdgcn_mfma_f32_16x16x32_bf16(a1[rb], b1, acc[rb], 0, 0, 0);
;             b0 = nb0; b1 = nb1;
; #pragma unroll
;             for (int rb = 0; rb < RB; ++rb) { a0[rb] = na0[rb]; a1[rb] = na1[rb]; }
;         }
; #pragma unroll
;         for (int rb = 0; rb < RB; ++rb)
; #pragma unroll
;             for (int j = 0; j < 4; ++j) red[(wave * (RB * 16) + rb * 16 + 4 * fq + j) * 16 + fr] = acc[rb][j];
;         __syncthreads();
.LBB0_122:
	s_ashr_i32 s4, s21, 31
	s_lshr_b32 s4, s4, 26
	s_add_i32 s4, s21, s4
	s_and_b32 s22, s4, 0xffffffc0
	s_lshl_b32 s4, s4, 4
	s_and_b32 s23, s4, 0xfffffc00
	s_sub_i32 s4, s10, s23
	v_add_u32_e32 v14, s4, v8
	v_ashrrev_i32_e32 v15, 31, v14
	v_lshlrev_b64 v[14:15], 12, v[14:15]
	v_lshl_add_u64 v[54:55], v[0:1], 0, v[14:15]
	v_or_b32_e32 v14, s22, v8
	v_ashrrev_i32_e32 v15, 31, v14
	v_lshlrev_b64 v[14:15], 12, v[14:15]
	v_lshl_add_u64 v[56:57], v[2:3], 0, v[14:15]
	v_add_co_u32_e64 v58, s[4:5], s18, v56
	s_nop 1
	v_addc_co_u32_e64 v59, s[4:5], 0, v57, s[4:5]
	v_add_co_u32_e64 v60, s[4:5], s19, v56
	s_nop 0
	s_nop 1
	v_addc_co_u32_e64 v61, s[4:5], 0, v57, s[4:5]
	v_add_co_u32_e64 v62, s[4:5], s20, v56
	s_nop 0
	s_nop 1
	v_addc_co_u32_e64 v63, s[4:5], 0, v57, s[4:5]
	global_load_dwordx4 v[32:35], v[54:55], off
	global_load_dwordx4 v[36:39], v[56:57], off
	global_load_dwordx4 v[40:43], v[58:59], off
	global_load_dwordx4 v[44:47], v[60:61], off
	global_load_dwordx4 v[48:51], v[62:63], off
	global_load_dwordx4 v[196:199], v[56:57], off offset:64
	global_load_dwordx4 v[200:203], v[54:55], off offset:64
	global_load_dwordx4 v[208:211], v[58:59], off offset:64
	global_load_dwordx4 v[212:215], v[60:61], off offset:64
	global_load_dwordx4 v[216:219], v[62:63], off offset:64
	global_load_dwordx4 v[220:223], v[56:57], off offset:128
	global_load_dwordx4 v[224:227], v[54:55], off offset:128
	global_load_dwordx4 v[228:231], v[54:55], off offset:192
	global_load_dwordx4 v[232:235], v[58:59], off offset:128
	global_load_dwordx4 v[236:239], v[60:61], off offset:128
	global_load_dwordx4 v[240:243], v[62:63], off offset:128
	global_load_dwordx4 v[244:247], v[62:63], off offset:192
	global_load_dwordx4 v[248:251], v[56:57], off offset:192
	s_waitcnt vmcnt(16)
	v_mfma_f32_16x16x32_bf16 v[16:19], v[36:39], v[32:35], 0
	global_load_dwordx4 v[36:39], v[58:59], off offset:192
	s_waitcnt vmcnt(16)
	v_mfma_f32_16x16x32_bf16 v[20:23], v[40:43], v[32:35], 0
	global_load_dwordx4 v[40:43], v[60:61], off offset:192
	s_waitcnt vmcnt(16)
	v_mfma_f32_16x16x32_bf16 v[24:27], v[44:47], v[32:35], 0
	global_load_dwordx4 v[44:47], v[56:57], off offset:256
	s_waitcnt vmcnt(16)
	v_mfma_f32_16x16x32_bf16 v[28:31], v[48:51], v[32:35], 0
	global_load_dwordx4 v[32:35], v[54:55], off offset:256
	global_load_dwordx4 v[48:51], v[54:55], off offset:320
	s_waitcnt vmcnt(16)
	v_mfma_f32_16x16x32_bf16 v[16:19], v[196:199], v[200:203], v[16:19]
	global_load_dwordx4 v[196:199], v[58:59], off offset:256
	s_waitcnt vmcnt(16)
	v_mfma_f32_16x16x32_bf16 v[20:23], v[208:211], v[200:203], v[20:23]
	global_load_dwordx4 v[208:211], v[60:61], off offset:256
	s_waitcnt vmcnt(16)
	v_mfma_f32_16x16x32_bf16 v[24:27], v[212:215], v[200:203], v[24:27]
	global_load_dwordx4 v[212:215], v[62:63], off offset:256
	s_waitcnt vmcnt(16)
	v_mfma_f32_16x16x32_bf16 v[28:31], v[216:219], v[200:203], v[28:31]
	global_load_dwordx4 v[216:219], v[62:63], off offset:320
	global_load_dwordx4 v[200:203], v[56:57], off offset:320
	s_waitcnt vmcnt(16)
	v_mfma_f32_16x16x32_bf16 v[16:19], v[220:223], v[224:227], v[16:19]
	global_load_dwordx4 v[220:223], v[58:59], off offset:320
	s_waitcnt vmcnt(15)
	v_mfma_f32_16x16x32_bf16 v[20:23], v[232:235], v[224:227], v[20:23]
	global_load_dwordx4 v[232:235], v[60:61], off offset:320
	s_waitcnt vmcnt(15)
	v_mfma_f32_16x16x32_bf16 v[24:27], v[236:239], v[224:227], v[24:27]
	global_load_dwordx4 v[236:239], v[56:57], off offset:384
	s_waitcnt vmcnt(15)
	v_mfma_f32_16x16x32_bf16 v[28:31], v[240:243], v[224:227], v[28:31]
	global_load_dwordx4 v[224:227], v[54:55], off offset:384
	global_load_dwordx4 v[240:243], v[54:55], off offset:448
	s_waitcnt vmcnt(15)
	v_mfma_f32_16x16x32_bf16 v[16:19], v[248:251], v[228:231], v[16:19]
	global_load_dwordx4 v[248:251], v[58:59], off offset:384
	s_waitcnt vmcnt(15)
	v_mfma_f32_16x16x32_bf16 v[20:23], v[36:39], v[228:231], v[20:23]
	global_load_dwordx4 v[36:39], v[60:61], off offset:384
	s_waitcnt vmcnt(15)
	v_mfma_f32_16x16x32_bf16 v[24:27], v[40:43], v[228:231], v[24:27]
	global_load_dwordx4 v[40:43], v[62:63], off offset:384
	v_mfma_f32_16x16x32_bf16 v[28:31], v[244:247], v[228:231], v[28:31]
	global_load_dwordx4 v[244:247], v[62:63], off offset:448
	global_load_dwordx4 v[228:231], v[56:57], off offset:448
	s_waitcnt vmcnt(16)
	v_mfma_f32_16x16x32_bf16 v[16:19], v[44:47], v[32:35], v[16:19]
	global_load_dwordx4 v[44:47], v[58:59], off offset:448
	s_waitcnt vmcnt(15)
	v_mfma_f32_16x16x32_bf16 v[20:23], v[196:199], v[32:35], v[20:23]
	global_load_dwordx4 v[196:199], v[60:61], off offset:448
	s_waitcnt vmcnt(15)
	v_mfma_f32_16x16x32_bf16 v[24:27], v[208:211], v[32:35], v[24:27]
	s_waitcnt vmcnt(14)
	v_mfma_f32_16x16x32_bf16 v[28:31], v[212:215], v[32:35], v[28:31]
	s_waitcnt vmcnt(12)
	v_mfma_f32_16x16x32_bf16 v[16:19], v[200:203], v[48:51], v[16:19]
	s_waitcnt vmcnt(11)
	v_mfma_f32_16x16x32_bf16 v[20:23], v[220:223], v[48:51], v[20:23]
	s_waitcnt vmcnt(10)
	v_mfma_f32_16x16x32_bf16 v[24:27], v[232:235], v[48:51], v[24:27]
	v_mfma_f32_16x16x32_bf16 v[28:31], v[216:219], v[48:51], v[28:31]
	s_waitcnt vmcnt(8)
	v_mfma_f32_16x16x32_bf16 v[16:19], v[236:239], v[224:227], v[16:19]
	s_waitcnt vmcnt(6)
	v_mfma_f32_16x16x32_bf16 v[20:23], v[248:251], v[224:227], v[20:23]
	s_waitcnt vmcnt(5)
	v_mfma_f32_16x16x32_bf16 v[24:27], v[36:39], v[224:227], v[24:27]
	s_waitcnt vmcnt(4)
	v_mfma_f32_16x16x32_bf16 v[28:31], v[40:43], v[224:227], v[28:31]
	s_waitcnt vmcnt(2)
	v_mfma_f32_16x16x32_bf16 v[16:19], v[228:231], v[240:243], v[16:19]
	s_waitcnt vmcnt(1)
	v_mfma_f32_16x16x32_bf16 v[20:23], v[44:47], v[240:243], v[20:23]
	v_mfma_f32_16x16x32_bf16 v[28:31], v[244:247], v[240:243], v[28:31]
	s_waitcnt vmcnt(0)
	v_mfma_f32_16x16x32_bf16 v[24:27], v[196:199], v[240:243], v[24:27]
	s_nop 7
	s_nop 1
	ds_write2_b32 v4, v16, v17 offset1:16
	ds_write2_b32 v4, v18, v19 offset0:32 offset1:48
	ds_write2_b32 v5, v20, v21 offset1:16
	ds_write2_b32 v5, v22, v23 offset0:32 offset1:48
	ds_write2_b32 v11, v24, v25 offset1:16
	ds_write2_b32 v11, v26, v27 offset0:32 offset1:48
	ds_write2_b32 v12, v28, v29 offset1:16
	ds_write2_b32 v12, v30, v31 offset0:32 offset1:48
	s_waitcnt lgkmcnt(0)
	s_barrier
; #define LAS __attribute__((address_space(3)))
;     ...
;         if (tid < RB * 64) { const int e = tid * 4, row = e >> 4, col = e & 15;
;             f32x4 v = *(const LAS f32x4*)(red + row * 16 + col);
; #pragma unroll
;             for (int w = 1; w < 8; ++w) v += *(const LAS f32x4*)(red + (w * (RB * 16) + row) * 16 + col);
;             E(rin + row, rh, ct * 16 + col, v); }
	s_and_saveexec_b64 s[4:5], vcc
	s_cbranch_execz .LBB0_121
	ds_read_b128 v[14:17], v10
	ds_read_b128 v[18:21], v10 offset:4096
	ds_read_b128 v[22:25], v10 offset:8192
	ds_read_b128 v[26:29], v10 offset:12288
	s_sub_i32 s16, 0, s23
	s_add_i32 s16, s16, s10
	s_waitcnt lgkmcnt(2)
	v_pk_add_f32 v[16:17], v[16:17], v[20:21]
	v_pk_add_f32 v[18:19], v[14:15], v[18:19]
	s_waitcnt lgkmcnt(1)
	v_pk_add_f32 v[20:21], v[16:17], v[24:25]
	ds_read_b128 v[14:17], v10 offset:16384
	v_pk_add_f32 v[18:19], v[18:19], v[22:23]
	s_waitcnt lgkmcnt(1)
	v_pk_add_f32 v[22:23], v[20:21], v[28:29]
	v_pk_add_f32 v[26:27], v[18:19], v[26:27]
	ds_read_b128 v[18:21], v10 offset:20480
	s_waitcnt lgkmcnt(1)
	v_pk_add_f32 v[28:29], v[22:23], v[16:17]
	ds_read_b128 v[22:25], v10 offset:24576
	v_pk_add_f32 v[26:27], v[26:27], v[14:15]
	ds_read_b128 v[14:17], v10 offset:28672
	s_waitcnt lgkmcnt(2)
	v_pk_add_f32 v[20:21], v[28:29], v[20:21]
	v_pk_add_f32 v[18:19], v[26:27], v[18:19]
	s_waitcnt lgkmcnt(1)
	v_pk_add_f32 v[20:21], v[20:21], v[24:25]
	v_pk_add_f32 v[18:19], v[18:19], v[22:23]
	s_waitcnt lgkmcnt(0)
	v_pk_add_f32 v[16:17], v[20:21], v[16:17]
	v_or_b32_e32 v20, s22, v6
	v_ashrrev_i32_e32 v21, 31, v20
	v_pk_add_f32 v[14:15], v[18:19], v[14:15]
	v_add_u32_e32 v18, s16, v7
	v_lshlrev_b64 v[20:21], 12, v[20:21]
	v_lshl_add_u64 v[20:21], s[6:7], 0, v[20:21]
	v_ashrrev_i32_e32 v19, 31, v18
	v_lshl_add_u64 v[18:19], v[18:19], 2, v[20:21]
	global_store_dwordx4 v[18:19], v[14:17], off
	s_branch .LBB0_121

;     ...
;         const bf16_t* bp = Wt + (size_t)(ct * 16 + fr) * ldb + wave * kw + fq * 8;
;         const bf16_t* ap = A + (size_t)(row0 + fr) * lda + wave * kw + fq * 8;
;         bf16x8 b0 = *(const bf16x8*)(bp), b1 = *(const bf16x8*)(bp + 32), a0[RB], a1[RB];
; #pragma unroll
;         for (int rb = 0; rb < RB; ++rb) { a0[rb] = *(const bf16x8*)(ap + (size_t)rb * 16 * lda); a1[rb] = *(const bf16x8*)(ap + (size_t)rb * 16 * lda + 32); }
;         for (int k = 0; k < kw; k += 64) {
;             bf16x8 nb0 = b0, nb1 = b1, na0[RB], na1[RB];
; #pragma unroll
;             for (int rb = 0; rb < RB; ++rb) { na0[rb] = a0[rb]; na1[rb] = a1[rb]; }
;             if (k + 64 < kw) {
;                 nb0 = *(const bf16x8*)(bp + k + 64); nb1 = *(const bf16x8*)(bp + k + 96);
; #pragma unroll
;                 for (int rb = 0; rb < RB; ++rb) { na0[rb] = *(const bf16x8*)(ap + (size_t)rb * 16 * lda + k + 64); na1[rb] = *(const bf16x8*)(ap + (size_t)rb * 16 * lda + k + 96); }
;             }
; #pragma unroll
;             for (int rb = 0; rb < RB; ++rb) acc[rb] = __builtin_amdgcn_mfma_f32_16x16x32_bf16(a0[rb], b0, acc[rb], 0, 0, 0);
; #pragma unroll
;             for (int rb = 0; rb < RB; ++rb) acc[rb] = __builtin_amdgcn_mfma_f32_16x16x32_bf16(a1[rb], b1, acc[rb], 0, 0, 0);
;             b0 = nb0; b1 = nb1;
; #pragma unroll
;             for (int rb = 0; rb < RB; ++rb) { a0[rb] = na0[rb]; a1[rb] = na1[rb]; }
;         }
; #pragma unroll
;         for (int rb = 0; rb < RB; ++rb)
; #pragma unroll
;             for (int j = 0; j < 4; ++j) red[(wave * (RB * 16) + rb * 16 + 4 * fq + j) * 16 + fr] = acc[rb][j];
.LBB0_496:
	s_ashr_i32 s6, s35, 31
	s_lshr_b32 s6, s6, 25
	s_add_i32 s6, s35, s6
	s_ashr_i32 s6, s6, 7
	s_lshl_b32 s41, s6, 6
	v_or_b32_e32 v16, s41, v196
	v_ashrrev_i32_e32 v17, 31, v16
	s_lshl_b32 s44, s6, 11
	v_lshlrev_b64 v[16:17], 12, v[16:17]
	s_sub_i32 s6, s28, s44
	v_lshl_add_u64 v[48:49], v[4:5], 0, v[16:17]
	v_add_u32_e32 v20, s6, v196
	v_add_co_u32_e64 v52, s[6:7], s31, v48
	v_ashrrev_i32_e32 v21, 31, v20
	s_nop 0
	v_addc_co_u32_e64 v53, s[6:7], 0, v49, s[6:7]
	v_add_co_u32_e64 v54, s[6:7], s34, v48
	v_lshlrev_b64 v[20:21], 12, v[20:21]
	s_nop 0
	v_addc_co_u32_e64 v55, s[6:7], 0, v49, s[6:7]
	v_add_co_u32_e64 v56, s[6:7], s30, v48
	v_lshl_add_u64 v[50:51], v[2:3], 0, v[20:21]
	s_nop 0
	v_addc_co_u32_e64 v57, s[6:7], 0, v49, s[6:7]
	global_load_dwordx4 v[38:41], v[48:49], off
	global_load_dwordx4 v[42:45], v[48:49], off offset:64
	global_load_dwordx4 v[118:121], v[50:51], off
	global_load_dwordx4 v[122:125], v[52:53], off
	global_load_dwordx4 v[126:129], v[54:55], off
	global_load_dwordx4 v[130:133], v[52:53], off offset:64
	global_load_dwordx4 v[134:137], v[56:57], off
	global_load_dwordx4 v[138:141], v[54:55], off offset:64
	global_load_dwordx4 v[142:145], v[50:51], off offset:64
	global_load_dwordx4 v[146:149], v[56:57], off offset:64
	global_load_dwordx4 v[150:153], v[48:49], off offset:128
	global_load_dwordx4 v[154:157], v[50:51], off offset:128
	global_load_dwordx4 v[158:161], v[50:51], off offset:192
	global_load_dwordx4 v[162:165], v[52:53], off offset:128
	global_load_dwordx4 v[166:169], v[54:55], off offset:128
	global_load_dwordx4 v[170:173], v[56:57], off offset:128
	global_load_dwordx4 v[174:177], v[56:57], off offset:192
	global_load_dwordx4 v[178:181], v[48:49], off offset:192
	global_load_dwordx4 v[182:185], v[52:53], off offset:192
	global_load_dwordx4 v[186:189], v[54:55], off offset:192
	global_load_dwordx4 v[198:201], v[48:49], off offset:256
	global_load_dwordx4 v[202:205], v[50:51], off offset:256
	global_load_dwordx4 v[210:213], v[50:51], off offset:320
	global_load_dwordx4 v[214:217], v[52:53], off offset:256
	global_load_dwordx4 v[218:221], v[54:55], off offset:256
	global_load_dwordx4 v[222:225], v[56:57], off offset:256
	global_load_dwordx4 v[226:229], v[56:57], off offset:320
	global_load_dwordx4 v[230:233], v[48:49], off offset:320
	global_load_dwordx4 v[234:237], v[52:53], off offset:320
	global_load_dwordx4 v[238:241], v[54:55], off offset:320
	global_load_dwordx4 v[242:245], v[48:49], off offset:384
	global_load_dwordx4 v[246:249], v[50:51], off offset:384
	global_load_dwordx4 v[250:253], v[50:51], off offset:448
	s_waitcnt vmcnt(28)
	v_mfma_f32_16x16x32_bf16 v[22:25], v[126:129], v[118:121], 0
	global_load_dwordx4 v[126:129], v[52:53], off offset:384
	v_mfma_f32_16x16x32_bf16 v[26:29], v[38:41], v[118:121], 0
	global_load_dwordx4 v[38:41], v[54:55], off offset:384
	v_mfma_f32_16x16x32_bf16 v[30:33], v[122:125], v[118:121], 0
	global_load_dwordx4 v[122:125], v[56:57], off offset:384
	s_waitcnt vmcnt(29)
	v_mfma_f32_16x16x32_bf16 v[34:37], v[134:137], v[118:121], 0
	global_load_dwordx4 v[118:121], v[56:57], off offset:448
	global_load_dwordx4 v[134:137], v[48:49], off offset:448
	s_waitcnt vmcnt(29)
	v_mfma_f32_16x16x32_bf16 v[26:29], v[42:45], v[142:145], v[26:29]
	global_load_dwordx4 v[42:45], v[52:53], off offset:448
	v_mfma_f32_16x16x32_bf16 v[30:33], v[130:133], v[142:145], v[30:33]
	global_load_dwordx4 v[130:133], v[54:55], off offset:448
	v_mfma_f32_16x16x32_bf16 v[22:25], v[138:141], v[142:145], v[22:25]
	s_waitcnt vmcnt(30)
	v_mfma_f32_16x16x32_bf16 v[34:37], v[146:149], v[142:145], v[34:37]
	s_waitcnt vmcnt(28)
	v_mfma_f32_16x16x32_bf16 v[26:29], v[150:153], v[154:157], v[26:29]
	s_waitcnt vmcnt(26)
	v_mfma_f32_16x16x32_bf16 v[30:33], v[162:165], v[154:157], v[30:33]
	s_waitcnt vmcnt(25)
	v_mfma_f32_16x16x32_bf16 v[22:25], v[166:169], v[154:157], v[22:25]
	s_waitcnt vmcnt(24)
	v_mfma_f32_16x16x32_bf16 v[34:37], v[170:173], v[154:157], v[34:37]
	s_waitcnt vmcnt(23)
	v_mfma_f32_16x16x32_bf16 v[34:37], v[174:177], v[158:161], v[34:37]
	s_waitcnt vmcnt(22)
	v_mfma_f32_16x16x32_bf16 v[26:29], v[178:181], v[158:161], v[26:29]
	s_waitcnt vmcnt(21)
	v_mfma_f32_16x16x32_bf16 v[30:33], v[182:185], v[158:161], v[30:33]
	s_waitcnt vmcnt(20)
	v_mfma_f32_16x16x32_bf16 v[22:25], v[186:189], v[158:161], v[22:25]
	s_waitcnt vmcnt(18)
	v_mfma_f32_16x16x32_bf16 v[26:29], v[198:201], v[202:205], v[26:29]
	s_waitcnt vmcnt(16)
	v_mfma_f32_16x16x32_bf16 v[30:33], v[214:217], v[202:205], v[30:33]
	s_waitcnt vmcnt(15)
	v_mfma_f32_16x16x32_bf16 v[22:25], v[218:221], v[202:205], v[22:25]
	s_waitcnt vmcnt(14)
	v_mfma_f32_16x16x32_bf16 v[34:37], v[222:225], v[202:205], v[34:37]
	s_waitcnt vmcnt(13)
	v_mfma_f32_16x16x32_bf16 v[34:37], v[226:229], v[210:213], v[34:37]
	s_waitcnt vmcnt(12)
	v_mfma_f32_16x16x32_bf16 v[26:29], v[230:233], v[210:213], v[26:29]
	s_waitcnt vmcnt(11)
	v_mfma_f32_16x16x32_bf16 v[30:33], v[234:237], v[210:213], v[30:33]
	s_waitcnt vmcnt(10)
	v_mfma_f32_16x16x32_bf16 v[22:25], v[238:241], v[210:213], v[22:25]
	s_waitcnt vmcnt(8)
	v_mfma_f32_16x16x32_bf16 v[26:29], v[242:245], v[246:249], v[26:29]
	s_waitcnt vmcnt(6)
	v_mfma_f32_16x16x32_bf16 v[30:33], v[126:129], v[246:249], v[30:33]
	s_waitcnt vmcnt(5)
	v_mfma_f32_16x16x32_bf16 v[22:25], v[38:41], v[246:249], v[22:25]
	s_waitcnt vmcnt(4)
	v_mfma_f32_16x16x32_bf16 v[34:37], v[122:125], v[246:249], v[34:37]
	s_waitcnt vmcnt(2)
	v_mfma_f32_16x16x32_bf16 v[26:29], v[134:137], v[250:253], v[26:29]
	s_waitcnt vmcnt(1)
	v_mfma_f32_16x16x32_bf16 v[30:33], v[42:45], v[250:253], v[30:33]
	s_waitcnt vmcnt(0)
	v_mfma_f32_16x16x32_bf16 v[22:25], v[130:133], v[250:253], v[22:25]
	v_mfma_f32_16x16x32_bf16 v[34:37], v[118:121], v[250:253], v[34:37]
	s_nop 7
	s_nop 1
	ds_write2_b32 v11, v26, v27 offset1:16
	ds_write2_b32 v11, v28, v29 offset0:32 offset1:48
	ds_write2_b32 v12, v30, v31 offset1:16
	ds_write2_b32 v12, v32, v33 offset0:32 offset1:48
	ds_write2_b32 v13, v22, v23 offset1:16
	ds_write2_b32 v13, v24, v25 offset0:32 offset1:48
	ds_write2_b32 v14, v34, v35 offset1:16
	ds_write2_b32 v14, v36, v37 offset0:32 offset1:48
	s_waitcnt lgkmcnt(0)
	s_barrier
; #define LAS __attribute__((address_space(3)))
;     ...
;         __syncthreads();
;         if (tid < RB * 64) { const int e = tid * 4, row = e >> 4, col = e & 15;
;             f32x4 v = *(const LAS f32x4*)(red + row * 16 + col);
; #pragma unroll
;             for (int w = 1; w < 8; ++w) v += *(const LAS f32x4*)(red + (w * (RB * 16) + row) * 16 + col);
;             E(rin + row, rh, ct * 16 + col, v); }
;         __syncthreads();
;     }
; }
	s_and_saveexec_b64 s[22:23], vcc
	s_cbranch_execz .LBB0_495
	s_sub_i32 s6, 0, s44
	s_add_i32 s6, s6, s28
	v_and_or_b32 v16, s41, 64, v6
	v_add_u32_e32 v54, s6, v7
	v_lshlrev_b32_e32 v0, 13, v16
	v_ashrrev_i32_e32 v55, 31, v54
	v_lshl_add_u64 v[18:19], s[12:13], 0, v[0:1]
	v_lshlrev_b64 v[56:57], 2, v[54:55]
	v_lshl_add_u64 v[18:19], v[18:19], 0, v[56:57]
	global_load_dwordx4 v[18:21], v[18:19], off
	ds_read_b128 v[22:25], v10
	ds_read_b128 v[26:29], v10 offset:4096
	ds_read_b128 v[30:33], v10 offset:8192
	ds_read_b128 v[34:37], v10 offset:12288
	ds_read_b128 v[38:41], v10 offset:16384
	ds_read_b128 v[42:45], v10 offset:20480
	ds_read_b128 v[46:49], v10 offset:24576
	ds_read_b128 v[50:53], v10 offset:28672
	s_waitcnt lgkmcnt(6)
	v_pk_add_f32 v[24:25], v[24:25], v[28:29]
	v_pk_add_f32 v[22:23], v[22:23], v[26:27]
	s_waitcnt lgkmcnt(5)
	v_pk_add_f32 v[24:25], v[24:25], v[32:33]
	v_pk_add_f32 v[22:23], v[22:23], v[30:31]
	s_waitcnt lgkmcnt(4)
	v_pk_add_f32 v[24:25], v[24:25], v[36:37]
	v_pk_add_f32 v[22:23], v[22:23], v[34:35]
	s_waitcnt lgkmcnt(3)
	v_pk_add_f32 v[24:25], v[24:25], v[40:41]
	v_pk_add_f32 v[22:23], v[22:23], v[38:39]
	s_waitcnt lgkmcnt(2)
	v_pk_add_f32 v[24:25], v[24:25], v[44:45]
	v_pk_add_f32 v[22:23], v[22:23], v[42:43]
	v_and_b32_e32 v58, 64, v15
	s_waitcnt lgkmcnt(1)
	v_pk_add_f32 v[24:25], v[24:25], v[48:49]
	v_pk_add_f32 v[22:23], v[22:23], v[46:47]
	v_xor_b32_e32 v17, 1, v15
	v_add_u32_e32 v61, 64, v58
	s_waitcnt lgkmcnt(0)
	v_pk_add_f32 v[24:25], v[24:25], v[52:53]
	v_pk_add_f32 v[22:23], v[22:23], v[50:51]
	v_cmp_lt_i32_e64 s[6:7], v17, v61
	v_lshl_add_u64 v[58:59], s[14:15], 0, v[0:1]
	v_xor_b32_e32 v60, 2, v15
	v_cndmask_b32_e64 v0, v15, v17, s[6:7]
	v_lshlrev_b32_e32 v0, 2, v0
	v_cmp_lt_i32_e64 s[6:7], v60, v61
	s_waitcnt vmcnt(0)
	v_pk_add_f32 v[20:21], v[24:25], v[20:21]
	v_pk_add_f32 v[18:19], v[22:23], v[18:19]
	v_mul_f32_e32 v22, v21, v21
	v_mul_f32_e32 v17, v19, v19
	v_fmac_f32_e32 v17, v18, v18
	v_fmac_f32_e32 v22, v20, v20
	v_add_f32_e32 v17, v17, v22
	ds_bpermute_b32 v0, v0, v17
	v_cndmask_b32_e64 v60, v15, v60, s[6:7]
	v_lshl_add_u64 v[22:23], v[58:59], 0, v[56:57]
	global_store_dwordx4 v[22:23], v[18:21], off
	v_cvt_pk_bf16_f32 v22, v18, v19
	s_waitcnt lgkmcnt(0)
	v_add_f32_e32 v17, v17, v0
	v_lshlrev_b32_e32 v0, 2, v60
	ds_bpermute_b32 v18, v0, v17
	v_lshlrev_b32_e32 v0, 12, v16
	v_cvt_pk_bf16_f32 v23, v20, v21
	v_lshl_add_u64 v[20:21], s[18:19], 0, v[0:1]
	v_lshl_add_u64 v[20:21], v[54:55], 1, v[20:21]
	global_store_dwordx2 v[20:21], v[22:23], off
	s_and_b64 exec, exec, s[4:5]
	s_cbranch_execz .LBB0_495
	v_lshlrev_b32_e32 v0, 2, v16
	s_waitcnt lgkmcnt(0)
	v_add_f32_e32 v16, v17, v18
	global_atomic_add_f32 v0, v16, s[20:21]
	s_branch .LBB0_495

; #define LAS __attribute__((address_space(3)))
;     ...
;         const bf16_t* bp = Wt + (size_t)(ct * 16 + fr) * ldb + wave * kw + fq * 8;
;         const bf16_t* ap = A + (size_t)(row0 + fr) * lda + wave * kw + fq * 8;
;         bf16x8 b0 = *(const bf16x8*)(bp), b1 = *(const bf16x8*)(bp + 32), a0[RB], a1[RB];
; #pragma unroll
;         for (int rb = 0; rb < RB; ++rb) { a0[rb] = *(const bf16x8*)(ap + (size_t)rb * 16 * lda); a1[rb] = *(const bf16x8*)(ap + (size_t)rb * 16 * lda + 32); }
;         for (int k = 0; k < kw; k += 64) {
;             bf16x8 nb0 = b0, nb1 = b1, na0[RB], na1[RB];
; #pragma unroll
;             for (int rb = 0; rb < RB; ++rb) { na0[rb] = a0[rb]; na1[rb] = a1[rb]; }
;             if (k + 64 < kw) {
;                 nb0 = *(const bf16x8*)(bp + k + 64); nb1 = *(const bf16x8*)(bp + k + 96);
; #pragma unroll
;                 for (int rb = 0; rb < RB; ++rb) { na0[rb] = *(const bf16x8*)(ap + (size_t)rb * 16 * lda + k + 64); na1[rb] = *(const bf16x8*)(ap + (size_t)rb * 16 * lda + k + 96); }
;             }
; #pragma unroll
;             for (int rb = 0; rb < RB; ++rb) acc[rb] = __builtin_amdgcn_mfma_f32_16x16x32_bf16(a0[rb], b0, acc[rb], 0, 0, 0);
; #pragma unroll
;             for (int rb = 0; rb < RB; ++rb) acc[rb] = __builtin_amdgcn_mfma_f32_16x16x32_bf16(a1[rb], b1, acc[rb], 0, 0, 0);
;             b0 = nb0; b1 = nb1;
; #pragma unroll
;             for (int rb = 0; rb < RB; ++rb) { a0[rb] = na0[rb]; a1[rb] = na1[rb]; }
;         }
; #pragma unroll
;         for (int rb = 0; rb < RB; ++rb)
; #pragma unroll
;             for (int j = 0; j < 4; ++j) red[(wave * (RB * 16) + rb * 16 + 4 * fq + j) * 16 + fr] = acc[rb][j];
;         __syncthreads();
;         if (tid < RB * 64) { const int e = tid * 4, row = e >> 4, col = e & 15;
;             f32x4 v = *(const LAS f32x4*)(red + row * 16 + col);
; #pragma unroll
;             for (int w = 1; w < 8; ++w) v += *(const LAS f32x4*)(red + (w * (RB * 16) + row) * 16 + col);
;             E(rin + row, rh, ct * 16 + col, v); }
;         __syncthreads();
;     }
; }
.LBB0_614:
	s_ashr_i32 s4, s15, 31
	s_lshr_b32 s4, s4, 27
	s_add_i32 s4, s15, s4
	s_and_b32 s18, s4, 0xffffffe0
	s_lshl_b32 s4, s4, 4
	s_and_b32 s19, s4, 0xfffffe00
	s_sub_i32 s4, s12, s19
	v_add_u32_e32 v10, s4, v196
	v_ashrrev_i32_e32 v11, 31, v10
	v_lshlrev_b64 v[10:11], 12, v[10:11]
	v_lshl_add_u64 v[46:47], v[0:1], 0, v[10:11]
	v_or_b32_e32 v10, s18, v196
	v_ashrrev_i32_e32 v11, 31, v10
	v_lshlrev_b64 v[10:11], 12, v[10:11]
	v_lshl_add_u64 v[48:49], v[2:3], 0, v[10:11]
	v_add_co_u32_e64 v50, s[4:5], s14, v48
	s_nop 1
	v_addc_co_u32_e64 v51, s[4:5], 0, v49, s[4:5]
	global_load_dwordx4 v[20:23], v[48:49], off
	global_load_dwordx4 v[24:27], v[50:51], off
	global_load_dwordx4 v[28:31], v[46:47], off
	global_load_dwordx4 v[32:35], v[48:49], off offset:64
	global_load_dwordx4 v[36:39], v[50:51], off offset:64
	global_load_dwordx4 v[40:43], v[46:47], off offset:64
	global_load_dwordx4 v[118:121], v[48:49], off offset:128
	global_load_dwordx4 v[122:125], v[50:51], off offset:128
	global_load_dwordx4 v[126:129], v[46:47], off offset:128
	global_load_dwordx4 v[130:133], v[48:49], off offset:192
	global_load_dwordx4 v[134:137], v[50:51], off offset:192
	global_load_dwordx4 v[138:141], v[46:47], off offset:192
	global_load_dwordx4 v[142:145], v[48:49], off offset:256
	global_load_dwordx4 v[146:149], v[50:51], off offset:256
	global_load_dwordx4 v[150:153], v[46:47], off offset:256
	global_load_dwordx4 v[154:157], v[48:49], off offset:320
	global_load_dwordx4 v[158:161], v[50:51], off offset:320
	global_load_dwordx4 v[162:165], v[46:47], off offset:320
	global_load_dwordx4 v[166:169], v[48:49], off offset:384
	global_load_dwordx4 v[170:173], v[46:47], off offset:384
	global_load_dwordx4 v[174:177], v[50:51], off offset:384
	global_load_dwordx4 v[178:181], v[48:49], off offset:448
	global_load_dwordx4 v[182:185], v[46:47], off offset:448
	global_load_dwordx4 v[186:189], v[50:51], off offset:448
	s_waitcnt vmcnt(21)
	v_mfma_f32_16x16x32_bf16 v[12:15], v[24:27], v[28:31], 0
	v_mfma_f32_16x16x32_bf16 v[16:19], v[20:23], v[28:31], 0
	s_waitcnt vmcnt(18)
	v_mfma_f32_16x16x32_bf16 v[16:19], v[32:35], v[40:43], v[16:19]
	v_mfma_f32_16x16x32_bf16 v[12:15], v[36:39], v[40:43], v[12:15]
	s_waitcnt vmcnt(15)
	v_mfma_f32_16x16x32_bf16 v[16:19], v[118:121], v[126:129], v[16:19]
	v_mfma_f32_16x16x32_bf16 v[12:15], v[122:125], v[126:129], v[12:15]
	s_waitcnt vmcnt(12)
	v_mfma_f32_16x16x32_bf16 v[16:19], v[130:133], v[138:141], v[16:19]
	v_mfma_f32_16x16x32_bf16 v[12:15], v[134:137], v[138:141], v[12:15]
	s_waitcnt vmcnt(9)
	v_mfma_f32_16x16x32_bf16 v[16:19], v[142:145], v[150:153], v[16:19]
	v_mfma_f32_16x16x32_bf16 v[12:15], v[146:149], v[150:153], v[12:15]
	s_waitcnt vmcnt(6)
	v_mfma_f32_16x16x32_bf16 v[16:19], v[154:157], v[162:165], v[16:19]
	v_mfma_f32_16x16x32_bf16 v[12:15], v[158:161], v[162:165], v[12:15]
	s_waitcnt vmcnt(4)
	v_mfma_f32_16x16x32_bf16 v[16:19], v[166:169], v[170:173], v[16:19]
	s_waitcnt vmcnt(3)
	v_mfma_f32_16x16x32_bf16 v[12:15], v[174:177], v[170:173], v[12:15]
	s_waitcnt vmcnt(1)
	v_mfma_f32_16x16x32_bf16 v[16:19], v[178:181], v[182:185], v[16:19]
	s_waitcnt vmcnt(0)
	v_mfma_f32_16x16x32_bf16 v[12:15], v[186:189], v[182:185], v[12:15]
	s_nop 7
	s_nop 1
	ds_write2_b32 v7, v16, v17 offset1:16
	ds_write2_b32 v7, v18, v19 offset0:32 offset1:48
	ds_write2_b32 v9, v12, v13 offset1:16
	ds_write2_b32 v9, v14, v15 offset0:32 offset1:48
	s_waitcnt lgkmcnt(0)
	s_barrier
	s_and_saveexec_b64 s[4:5], vcc
	s_cbranch_execz .LBB0_613
	ds_read_b128 v[10:13], v6
	ds_read_b128 v[14:17], v6 offset:2048
	ds_read_b128 v[18:21], v6 offset:4096
	ds_read_b128 v[22:25], v6 offset:6144
	s_sub_i32 s16, 0, s19
	s_add_i32 s16, s16, s12
	s_waitcnt lgkmcnt(2)
	v_pk_add_f32 v[12:13], v[12:13], v[16:17]
	v_pk_add_f32 v[14:15], v[10:11], v[14:15]
	s_waitcnt lgkmcnt(1)
	v_pk_add_f32 v[16:17], v[12:13], v[20:21]
	ds_read_b128 v[10:13], v6 offset:8192
	v_pk_add_f32 v[14:15], v[14:15], v[18:19]
	s_waitcnt lgkmcnt(1)
	v_pk_add_f32 v[18:19], v[16:17], v[24:25]
	v_pk_add_f32 v[22:23], v[14:15], v[22:23]
	ds_read_b128 v[14:17], v6 offset:10240
	s_waitcnt lgkmcnt(1)
	v_pk_add_f32 v[24:25], v[18:19], v[12:13]
	ds_read_b128 v[18:21], v6 offset:12288
	v_pk_add_f32 v[22:23], v[22:23], v[10:11]
	ds_read_b128 v[10:13], v6 offset:14336
	s_waitcnt lgkmcnt(2)
	v_pk_add_f32 v[16:17], v[24:25], v[16:17]
	v_pk_add_f32 v[14:15], v[22:23], v[14:15]
	s_waitcnt lgkmcnt(1)
	v_pk_add_f32 v[16:17], v[16:17], v[20:21]
	v_pk_add_f32 v[14:15], v[14:15], v[18:19]
	s_waitcnt lgkmcnt(0)
	v_pk_add_f32 v[12:13], v[16:17], v[12:13]
	v_pk_add_f32 v[10:11], v[14:15], v[10:11]
	v_add_u32_e32 v14, s16, v5
	v_cvt_pk_bf16_f32 v10, v10, v11
	v_cvt_pk_bf16_f32 v11, v12, v13
	v_or_b32_e32 v12, s18, v4
	v_ashrrev_i32_e32 v13, 31, v12
	v_lshlrev_b64 v[12:13], 10, v[12:13]
	v_lshl_add_u64 v[12:13], s[10:11], 0, v[12:13]
	v_ashrrev_i32_e32 v15, 31, v14
	v_lshl_add_u64 v[12:13], v[14:15], 1, v[12:13]
	global_store_dwordx2 v[12:13], v[10:11], off
	s_branch .LBB0_613

; #define LAS __attribute__((address_space(3)))
;     ...
;         const bf16_t* bp = Wt + (size_t)(ct * 16 + fr) * ldb + wave * kw + fq * 8;
;         const bf16_t* ap = A + (size_t)(row0 + fr) * lda + wave * kw + fq * 8;
;         bf16x8 b0 = *(const bf16x8*)(bp), b1 = *(const bf16x8*)(bp + 32), a0[RB], a1[RB];
; #pragma unroll
;         for (int rb = 0; rb < RB; ++rb) { a0[rb] = *(const bf16x8*)(ap + (size_t)rb * 16 * lda); a1[rb] = *(const bf16x8*)(ap + (size_t)rb * 16 * lda + 32); }
;         for (int k = 0; k < kw; k += 64) {
;             bf16x8 nb0 = b0, nb1 = b1, na0[RB], na1[RB];
; #pragma unroll
;             for (int rb = 0; rb < RB; ++rb) { na0[rb] = a0[rb]; na1[rb] = a1[rb]; }
;             if (k + 64 < kw) {
;                 nb0 = *(const bf16x8*)(bp + k + 64); nb1 = *(const bf16x8*)(bp + k + 96);
; #pragma unroll
;                 for (int rb = 0; rb < RB; ++rb) { na0[rb] = *(const bf16x8*)(ap + (size_t)rb * 16 * lda + k + 64); na1[rb] = *(const bf16x8*)(ap + (size_t)rb * 16 * lda + k + 96); }
;             }
; #pragma unroll
;             for (int rb = 0; rb < RB; ++rb) acc[rb] = __builtin_amdgcn_mfma_f32_16x16x32_bf16(a0[rb], b0, acc[rb], 0, 0, 0);
; #pragma unroll
;             for (int rb = 0; rb < RB; ++rb) acc[rb] = __builtin_amdgcn_mfma_f32_16x16x32_bf16(a1[rb], b1, acc[rb], 0, 0, 0);
;             b0 = nb0; b1 = nb1;
; #pragma unroll
;             for (int rb = 0; rb < RB; ++rb) { a0[rb] = na0[rb]; a1[rb] = na1[rb]; }
;         }
; #pragma unroll
;         for (int rb = 0; rb < RB; ++rb)
; #pragma unroll
;             for (int j = 0; j < 4; ++j) red[(wave * (RB * 16) + rb * 16 + 4 * fq + j) * 16 + fr] = acc[rb][j];
;         __syncthreads();
;         if (tid < RB * 64) { const int e = tid * 4, row = e >> 4, col = e & 15;
;             f32x4 v = *(const LAS f32x4*)(red + row * 16 + col);
; #pragma unroll
;             for (int w = 1; w < 8; ++w) v += *(const LAS f32x4*)(red + (w * (RB * 16) + row) * 16 + col);
;             E(rin + row, rh, ct * 16 + col, v); }
;         __syncthreads();
;     }
; }
.LBB0_703:
	s_ashr_i32 s6, s29, 31
	s_lshr_b32 s6, s6, 25
	s_add_i32 s6, s29, s6
	s_ashr_i32 s6, s6, 7
	s_lshl_b32 s30, s6, 6
	v_or_b32_e32 v20, s30, v196
	v_ashrrev_i32_e32 v21, 31, v20
	s_lshl_b32 s31, s6, 11
	v_lshlrev_b64 v[20:21], 10, v[20:21]
	s_sub_i32 s6, s20, s31
	v_lshl_add_u64 v[44:45], v[4:5], 0, v[20:21]
	v_add_u32_e32 v24, s6, v196
	v_add_co_u32_e64 v46, s[6:7], s23, v44
	v_ashrrev_i32_e32 v25, 31, v24
	s_nop 0
	v_addc_co_u32_e64 v47, s[6:7], 0, v45, s[6:7]
	v_add_co_u32_e64 v48, s[6:7], s28, v44
	v_lshlrev_b64 v[24:25], 10, v[24:25]
	s_nop 0
	v_addc_co_u32_e64 v49, s[6:7], 0, v45, s[6:7]
	v_add_co_u32_e64 v54, s[6:7], s22, v44
	v_lshl_add_u64 v[52:53], v[2:3], 0, v[24:25]
	s_nop 0
	v_addc_co_u32_e64 v55, s[6:7], 0, v45, s[6:7]
	global_load_dwordx4 v[118:121], v[44:45], off
	global_load_dwordx4 v[122:125], v[44:45], off offset:64
	global_load_dwordx4 v[126:129], v[52:53], off
	global_load_dwordx4 v[130:133], v[46:47], off
	global_load_dwordx4 v[134:137], v[48:49], off
	global_load_dwordx4 v[138:141], v[46:47], off offset:64
	global_load_dwordx4 v[142:145], v[48:49], off offset:64
	global_load_dwordx4 v[146:149], v[54:55], off
	global_load_dwordx4 v[150:153], v[52:53], off offset:64
	global_load_dwordx4 v[154:157], v[54:55], off offset:64
	s_waitcnt vmcnt(5)
	v_mfma_f32_16x16x32_bf16 v[26:29], v[134:137], v[126:129], 0
	v_mfma_f32_16x16x32_bf16 v[30:33], v[118:121], v[126:129], 0
	v_mfma_f32_16x16x32_bf16 v[34:37], v[130:133], v[126:129], 0
	s_waitcnt vmcnt(2)
	v_mfma_f32_16x16x32_bf16 v[38:41], v[146:149], v[126:129], 0
	s_waitcnt vmcnt(1)
	v_mfma_f32_16x16x32_bf16 v[30:33], v[122:125], v[150:153], v[30:33]
	v_mfma_f32_16x16x32_bf16 v[26:29], v[142:145], v[150:153], v[26:29]
	v_mfma_f32_16x16x32_bf16 v[34:37], v[138:141], v[150:153], v[34:37]
	s_waitcnt vmcnt(0)
	v_mfma_f32_16x16x32_bf16 v[38:41], v[154:157], v[150:153], v[38:41]
	s_nop 7
	s_nop 1
	ds_write2_b32 v12, v30, v31 offset1:16
	ds_write2_b32 v12, v32, v33 offset0:32 offset1:48
	ds_write2_b32 v17, v34, v35 offset1:16
	ds_write2_b32 v17, v36, v37 offset0:32 offset1:48
	ds_write2_b32 v18, v26, v27 offset1:16
	ds_write2_b32 v18, v28, v29 offset0:32 offset1:48
	ds_write2_b32 v19, v38, v39 offset1:16
	ds_write2_b32 v19, v40, v41 offset0:32 offset1:48
	s_waitcnt lgkmcnt(0)
	s_barrier
	s_and_saveexec_b64 s[18:19], vcc
	s_cbranch_execz .LBB0_702
	s_sub_i32 s6, 0, s31
	v_and_or_b32 v20, s30, 64, v6
	s_add_i32 s6, s6, s20
	v_add_u32_e32 v58, s6, v7
	v_lshlrev_b32_e32 v0, 13, v20
	v_lshl_add_u64 v[22:23], s[10:11], 0, v[0:1]
	v_ashrrev_i32_e32 v59, 31, v58
	v_lshl_add_u64 v[60:61], v[58:59], 2, v[22:23]
	global_load_dwordx4 v[22:25], v[60:61], off
	ds_read_b128 v[26:29], v11
	ds_read_b128 v[30:33], v11 offset:4096
	ds_read_b128 v[34:37], v11 offset:8192
	ds_read_b128 v[38:41], v11 offset:12288
	ds_read_b128 v[42:45], v11 offset:16384
	ds_read_b128 v[46:49], v11 offset:20480
	ds_read_b128 v[50:53], v11 offset:24576
	ds_read_b128 v[54:57], v11 offset:28672
	s_waitcnt lgkmcnt(6)
	v_pk_add_f32 v[28:29], v[28:29], v[32:33]
	v_pk_add_f32 v[26:27], v[26:27], v[30:31]
	s_waitcnt lgkmcnt(5)
	v_pk_add_f32 v[28:29], v[28:29], v[36:37]
	v_pk_add_f32 v[26:27], v[26:27], v[34:35]
	s_waitcnt lgkmcnt(4)
	v_pk_add_f32 v[28:29], v[28:29], v[40:41]
	v_pk_add_f32 v[26:27], v[26:27], v[38:39]
	s_waitcnt lgkmcnt(3)
	v_pk_add_f32 v[28:29], v[28:29], v[44:45]
	v_pk_add_f32 v[26:27], v[26:27], v[42:43]
	s_waitcnt lgkmcnt(2)
	v_pk_add_f32 v[28:29], v[28:29], v[48:49]
	v_pk_add_f32 v[26:27], v[26:27], v[46:47]
	s_waitcnt lgkmcnt(1)
	v_pk_add_f32 v[28:29], v[28:29], v[52:53]
	v_pk_add_f32 v[26:27], v[26:27], v[50:51]
	s_waitcnt lgkmcnt(0)
	v_pk_add_f32 v[28:29], v[28:29], v[56:57]
	v_pk_add_f32 v[26:27], v[26:27], v[54:55]
	v_cmp_lt_i32_e64 s[6:7], v14, v15
	s_waitcnt vmcnt(0)
	v_pk_add_f32 v[24:25], v[28:29], v[24:25]
	v_pk_add_f32 v[22:23], v[26:27], v[22:23]
	v_mul_f32_e32 v26, v25, v25
	v_mul_f32_e32 v21, v23, v23
	v_cndmask_b32_e64 v0, v13, v14, s[6:7]
	v_fmac_f32_e32 v21, v22, v22
	v_fmac_f32_e32 v26, v24, v24
	v_lshlrev_b32_e32 v0, 2, v0
	v_add_f32_e32 v21, v21, v26
	ds_bpermute_b32 v0, v0, v21
	v_cmp_lt_i32_e64 s[6:7], v16, v15
	global_store_dwordx4 v[60:61], v[22:25], off
	v_cvt_pk_bf16_f32 v26, v22, v23
	v_cndmask_b32_e64 v28, v13, v16, s[6:7]
	s_waitcnt lgkmcnt(0)
	v_add_f32_e32 v21, v21, v0
	v_lshlrev_b32_e32 v0, 2, v28
	ds_bpermute_b32 v22, v0, v21
	v_lshlrev_b32_e32 v0, 12, v20
	v_cvt_pk_bf16_f32 v27, v24, v25
	v_lshl_add_u64 v[24:25], s[12:13], 0, v[0:1]
	v_lshl_add_u64 v[24:25], v[58:59], 1, v[24:25]
	global_store_dwordx2 v[24:25], v[26:27], off
	s_and_b64 exec, exec, s[4:5]
	s_cbranch_execz .LBB0_702
	v_lshlrev_b32_e32 v0, 2, v20
	s_waitcnt lgkmcnt(0)
	v_add_f32_e32 v20, v21, v22
	global_atomic_add_f32 v0, v20, s[14:15]
	s_branch .LBB0_702

;     ...
;         const bf16_t* bp = Wt + (size_t)(ct * 16 + fr) * ldb + wave * kw + fq * 8;
;         const bf16_t* ap = A + (size_t)(row0 + fr) * lda + wave * kw + fq * 8;
;         bf16x8 b0 = *(const bf16x8*)(bp), b1 = *(const bf16x8*)(bp + 32), a0[RB], a1[RB];
; #pragma unroll
;         for (int rb = 0; rb < RB; ++rb) { a0[rb] = *(const bf16x8*)(ap + (size_t)rb * 16 * lda); a1[rb] = *(const bf16x8*)(ap + (size_t)rb * 16 * lda + 32); }
;         for (int k = 0; k < kw; k += 64) {
;             bf16x8 nb0 = b0, nb1 = b1, na0[RB], na1[RB];
; #pragma unroll
;             for (int rb = 0; rb < RB; ++rb) { na0[rb] = a0[rb]; na1[rb] = a1[rb]; }
;             if (k + 64 < kw) {
;                 nb0 = *(const bf16x8*)(bp + k + 64); nb1 = *(const bf16x8*)(bp + k + 96);
; #pragma unroll
;                 for (int rb = 0; rb < RB; ++rb) { na0[rb] = *(const bf16x8*)(ap + (size_t)rb * 16 * lda + k + 64); na1[rb] = *(const bf16x8*)(ap + (size_t)rb * 16 * lda + k + 96); }
;             }
; #pragma unroll
;             for (int rb = 0; rb < RB; ++rb) acc[rb] = __builtin_amdgcn_mfma_f32_16x16x32_bf16(a0[rb], b0, acc[rb], 0, 0, 0);
; #pragma unroll
;             for (int rb = 0; rb < RB; ++rb) acc[rb] = __builtin_amdgcn_mfma_f32_16x16x32_bf16(a1[rb], b1, acc[rb], 0, 0, 0);
;             b0 = nb0; b1 = nb1;
; #pragma unroll
;             for (int rb = 0; rb < RB; ++rb) { a0[rb] = na0[rb]; a1[rb] = na1[rb]; }
;         }
.LBB0_872:
	s_ashr_i32 s0, s18, 31
	s_lshr_b32 s0, s0, 25
	s_add_i32 s0, s18, s0
	s_ashr_i32 s19, s0, 7
	s_lshl_b32 s20, s19, 6
	s_mul_i32 s21, s19, 0xff500000
	v_or_b32_e32 v0, s20, v196
	v_add_u32_e32 v8, s21, v19
	v_mad_i64_i32 v[6:7], s[0:1], v0, s14, v[4:5]
	v_ashrrev_i32_e32 v9, 31, v8
	v_lshl_add_u64 v[12:13], v[8:9], 1, v[2:3]
	v_add_co_u32_e64 v8, s[0:1], s15, v6
	s_nop 1
	v_addc_co_u32_e64 v9, s[0:1], 0, v7, s[0:1]
	v_add_co_u32_e64 v10, s[0:1], s16, v6
	s_nop 0
	s_nop 1
	v_addc_co_u32_e64 v11, s[0:1], 0, v7, s[0:1]
	v_add_co_u32_e64 v14, s[0:1], s17, v6
	s_nop 0
	s_nop 1
	v_addc_co_u32_e64 v15, s[0:1], 0, v7, s[0:1]
	global_load_dwordx4 v[42:45], v[6:7], off
	global_load_dwordx4 v[46:49], v[12:13], off
	global_load_dwordx4 v[50:53], v[6:7], off offset:64
	global_load_dwordx4 v[54:57], v[8:9], off
	global_load_dwordx4 v[58:61], v[12:13], off offset:64
	global_load_dwordx4 v[62:65], v[10:11], off
	global_load_dwordx4 v[66:69], v[8:9], off offset:64
	global_load_dwordx4 v[70:73], v[10:11], off offset:64
	global_load_dwordx4 v[74:77], v[14:15], off
	global_load_dwordx4 v[78:81], v[14:15], off offset:64
	global_load_dwordx4 v[82:85], v[6:7], off offset:128
	global_load_dwordx4 v[86:89], v[12:13], off offset:128
	global_load_dwordx4 v[90:93], v[8:9], off offset:128
	global_load_dwordx4 v[94:97], v[12:13], off offset:192
	global_load_dwordx4 v[98:101], v[10:11], off offset:128
	global_load_dwordx4 v[102:105], v[14:15], off offset:128
	global_load_dwordx4 v[106:109], v[6:7], off offset:192
	global_load_dwordx4 v[110:113], v[14:15], off offset:192
	global_load_dwordx4 v[114:117], v[8:9], off offset:192
	global_load_dwordx4 v[118:121], v[10:11], off offset:192
	global_load_dwordx4 v[122:125], v[6:7], off offset:256
	global_load_dwordx4 v[126:129], v[12:13], off offset:256
	global_load_dwordx4 v[130:133], v[8:9], off offset:256
	global_load_dwordx4 v[134:137], v[12:13], off offset:320
	global_load_dwordx4 v[138:141], v[10:11], off offset:256
	global_load_dwordx4 v[142:145], v[14:15], off offset:256
	global_load_dwordx4 v[146:149], v[6:7], off offset:320
	global_load_dwordx4 v[150:153], v[14:15], off offset:320
	global_load_dwordx4 v[154:157], v[8:9], off offset:320
	global_load_dwordx4 v[158:161], v[10:11], off offset:320
	global_load_dwordx4 v[162:165], v[6:7], off offset:384
	global_load_dwordx4 v[166:169], v[12:13], off offset:384
	global_load_dwordx4 v[170:173], v[8:9], off offset:384
	global_load_dwordx4 v[174:177], v[12:13], off offset:448
	global_load_dwordx4 v[178:181], v[10:11], off offset:384
	global_load_dwordx4 v[182:185], v[14:15], off offset:384
	global_load_dwordx4 v[186:189], v[6:7], off offset:448
	global_load_dwordx4 v[198:201], v[14:15], off offset:448
	global_load_dwordx4 v[202:205], v[8:9], off offset:448
	global_load_dwordx4 v[210:213], v[10:11], off offset:448
	global_load_dwordx4 v[214:217], v[6:7], off offset:512
	global_load_dwordx4 v[218:221], v[12:13], off offset:512
	global_load_dwordx4 v[222:225], v[8:9], off offset:512
	global_load_dwordx4 v[226:229], v[12:13], off offset:576
	global_load_dwordx4 v[230:233], v[10:11], off offset:512
	global_load_dwordx4 v[234:237], v[14:15], off offset:512
	global_load_dwordx4 v[238:241], v[6:7], off offset:576
	global_load_dwordx4 v[242:245], v[14:15], off offset:576
	global_load_dwordx4 v[246:249], v[8:9], off offset:576
	global_load_dwordx4 v[250:253], v[10:11], off offset:576
	s_waitcnt vmcnt(48)
	v_mfma_f32_16x16x32_bf16 v[26:29], v[42:45], v[46:49], 0
	global_load_dwordx4 v[42:45], v[6:7], off offset:640
	s_waitcnt vmcnt(47)
	v_mfma_f32_16x16x32_bf16 v[30:33], v[54:57], v[46:49], 0
	global_load_dwordx4 v[54:57], v[12:13], off offset:640
	s_waitcnt vmcnt(47)
	v_mfma_f32_16x16x32_bf16 v[26:29], v[50:53], v[58:61], v[26:29]
	global_load_dwordx4 v[50:53], v[8:9], off offset:640
	s_waitcnt vmcnt(46)
	v_mfma_f32_16x16x32_bf16 v[30:33], v[66:69], v[58:61], v[30:33]
	global_load_dwordx4 v[66:69], v[12:13], off offset:704
	v_mfma_f32_16x16x32_bf16 v[34:37], v[62:65], v[46:49], 0
	global_load_dwordx4 v[62:65], v[10:11], off offset:640
	s_waitcnt vmcnt(46)
	v_mfma_f32_16x16x32_bf16 v[38:41], v[74:77], v[46:49], 0
	global_load_dwordx4 v[74:77], v[14:15], off offset:640
	global_load_dwordx4 v[46:49], v[6:7], off offset:704
	v_mfma_f32_16x16x32_bf16 v[34:37], v[70:73], v[58:61], v[34:37]
	global_load_dwordx4 v[70:73], v[14:15], off offset:704
	s_waitcnt vmcnt(48)
	v_mfma_f32_16x16x32_bf16 v[38:41], v[78:81], v[58:61], v[38:41]
	global_load_dwordx4 v[78:81], v[8:9], off offset:704
	global_load_dwordx4 v[58:61], v[10:11], off offset:704
	s_waitcnt vmcnt(48)
	v_mfma_f32_16x16x32_bf16 v[26:29], v[82:85], v[86:89], v[26:29]
	global_load_dwordx4 v[82:85], v[6:7], off offset:768
	s_waitcnt vmcnt(48)
	v_mfma_f32_16x16x32_bf16 v[30:33], v[90:93], v[86:89], v[30:33]
	global_load_dwordx4 v[90:93], v[12:13], off offset:768
	s_waitcnt vmcnt(47)
	v_mfma_f32_16x16x32_bf16 v[34:37], v[98:101], v[86:89], v[34:37]
	global_load_dwordx4 v[98:101], v[8:9], off offset:768
	s_waitcnt vmcnt(47)
	v_mfma_f32_16x16x32_bf16 v[38:41], v[102:105], v[86:89], v[38:41]
	global_load_dwordx4 v[86:89], v[12:13], off offset:832
	global_load_dwordx4 v[102:105], v[10:11], off offset:768
	s_waitcnt vmcnt(48)
	v_mfma_f32_16x16x32_bf16 v[26:29], v[106:109], v[94:97], v[26:29]
	global_load_dwordx4 v[106:109], v[14:15], off offset:768
	s_waitcnt vmcnt(47)
	v_mfma_f32_16x16x32_bf16 v[30:33], v[114:117], v[94:97], v[30:33]
	global_load_dwordx4 v[114:117], v[6:7], off offset:832
	s_waitcnt vmcnt(47)
;     ...
;         for (int k = 0; k < kw; k += 64) {
;             bf16x8 nb0 = b0, nb1 = b1, na0[RB], na1[RB];
; #pragma unroll
;             for (int rb = 0; rb < RB; ++rb) { na0[rb] = a0[rb]; na1[rb] = a1[rb]; }
;             if (k + 64 < kw) {
;                 nb0 = *(const bf16x8*)(bp + k + 64); nb1 = *(const bf16x8*)(bp + k + 96);
; #pragma unroll
;                 for (int rb = 0; rb < RB; ++rb) { na0[rb] = *(const bf16x8*)(ap + (size_t)rb * 16 * lda + k + 64); na1[rb] = *(const bf16x8*)(ap + (size_t)rb * 16 * lda + k + 96); }
;             }
; #pragma unroll
;             for (int rb = 0; rb < RB; ++rb) acc[rb] = __builtin_amdgcn_mfma_f32_16x16x32_bf16(a0[rb], b0, acc[rb], 0, 0, 0);
; #pragma unroll
;             for (int rb = 0; rb < RB; ++rb) acc[rb] = __builtin_amdgcn_mfma_f32_16x16x32_bf16(a1[rb], b1, acc[rb], 0, 0, 0);
;             b0 = nb0; b1 = nb1;
; #pragma unroll
;             for (int rb = 0; rb < RB; ++rb) { a0[rb] = na0[rb]; a1[rb] = na1[rb]; }
;         }
	v_mfma_f32_16x16x32_bf16 v[34:37], v[118:121], v[94:97], v[34:37]
	global_load_dwordx4 v[118:121], v[14:15], off offset:832
	v_mfma_f32_16x16x32_bf16 v[38:41], v[110:113], v[94:97], v[38:41]
	global_load_dwordx4 v[110:113], v[8:9], off offset:832
	global_load_dwordx4 v[94:97], v[10:11], off offset:832
	s_waitcnt vmcnt(48)
	v_mfma_f32_16x16x32_bf16 v[26:29], v[122:125], v[126:129], v[26:29]
	global_load_dwordx4 v[122:125], v[6:7], off offset:896
	s_waitcnt vmcnt(48)
	v_mfma_f32_16x16x32_bf16 v[30:33], v[130:133], v[126:129], v[30:33]
	global_load_dwordx4 v[130:133], v[12:13], off offset:896
	s_waitcnt vmcnt(47)
	v_mfma_f32_16x16x32_bf16 v[34:37], v[138:141], v[126:129], v[34:37]
	global_load_dwordx4 v[138:141], v[8:9], off offset:896
	s_waitcnt vmcnt(47)
	v_mfma_f32_16x16x32_bf16 v[38:41], v[142:145], v[126:129], v[38:41]
	global_load_dwordx4 v[142:145], v[12:13], off offset:960
	global_load_dwordx4 v[126:129], v[10:11], off offset:896
	s_waitcnt vmcnt(48)
	v_mfma_f32_16x16x32_bf16 v[26:29], v[146:149], v[134:137], v[26:29]
	global_load_dwordx4 v[146:149], v[14:15], off offset:896
	s_waitcnt vmcnt(47)
	v_mfma_f32_16x16x32_bf16 v[30:33], v[154:157], v[134:137], v[30:33]
	global_load_dwordx4 v[154:157], v[6:7], off offset:960
	s_waitcnt vmcnt(47)
	v_mfma_f32_16x16x32_bf16 v[34:37], v[158:161], v[134:137], v[34:37]
	global_load_dwordx4 v[158:161], v[14:15], off offset:960
	v_mfma_f32_16x16x32_bf16 v[38:41], v[150:153], v[134:137], v[38:41]
	global_load_dwordx4 v[150:153], v[8:9], off offset:960
	global_load_dwordx4 v[134:137], v[10:11], off offset:960
	s_waitcnt vmcnt(48)
	v_mfma_f32_16x16x32_bf16 v[26:29], v[162:165], v[166:169], v[26:29]
	global_load_dwordx4 v[162:165], v[6:7], off offset:1024
	s_waitcnt vmcnt(48)
	v_mfma_f32_16x16x32_bf16 v[30:33], v[170:173], v[166:169], v[30:33]
	global_load_dwordx4 v[170:173], v[12:13], off offset:1024
	s_waitcnt vmcnt(47)
	v_mfma_f32_16x16x32_bf16 v[34:37], v[178:181], v[166:169], v[34:37]
	global_load_dwordx4 v[178:181], v[8:9], off offset:1024
	s_waitcnt vmcnt(47)
	v_mfma_f32_16x16x32_bf16 v[38:41], v[182:185], v[166:169], v[38:41]
	global_load_dwordx4 v[182:185], v[12:13], off offset:1088
	global_load_dwordx4 v[166:169], v[10:11], off offset:1024
	s_waitcnt vmcnt(48)
	v_mfma_f32_16x16x32_bf16 v[26:29], v[186:189], v[174:177], v[26:29]
	global_load_dwordx4 v[186:189], v[14:15], off offset:1024
	s_waitcnt vmcnt(47)
	v_mfma_f32_16x16x32_bf16 v[30:33], v[202:205], v[174:177], v[30:33]
	global_load_dwordx4 v[202:205], v[6:7], off offset:1088
	s_waitcnt vmcnt(47)
	v_mfma_f32_16x16x32_bf16 v[34:37], v[210:213], v[174:177], v[34:37]
	global_load_dwordx4 v[210:213], v[14:15], off offset:1088
	v_mfma_f32_16x16x32_bf16 v[38:41], v[198:201], v[174:177], v[38:41]
	global_load_dwordx4 v[174:177], v[8:9], off offset:1088
	global_load_dwordx4 v[198:201], v[10:11], off offset:1088
	s_waitcnt vmcnt(48)
	v_mfma_f32_16x16x32_bf16 v[26:29], v[214:217], v[218:221], v[26:29]
	global_load_dwordx4 v[214:217], v[6:7], off offset:1152
	s_waitcnt vmcnt(48)
	v_mfma_f32_16x16x32_bf16 v[30:33], v[222:225], v[218:221], v[30:33]
	global_load_dwordx4 v[222:225], v[12:13], off offset:1152
	s_waitcnt vmcnt(47)
	v_mfma_f32_16x16x32_bf16 v[34:37], v[230:233], v[218:221], v[34:37]
	global_load_dwordx4 v[230:233], v[8:9], off offset:1152
	s_waitcnt vmcnt(47)
	v_mfma_f32_16x16x32_bf16 v[38:41], v[234:237], v[218:221], v[38:41]
	global_load_dwordx4 v[218:221], v[12:13], off offset:1216
	global_load_dwordx4 v[234:237], v[10:11], off offset:1152
	s_waitcnt vmcnt(48)
	v_mfma_f32_16x16x32_bf16 v[26:29], v[238:241], v[226:229], v[26:29]
	global_load_dwordx4 v[238:241], v[14:15], off offset:1152
	s_waitcnt vmcnt(47)
	v_mfma_f32_16x16x32_bf16 v[30:33], v[246:249], v[226:229], v[30:33]
	global_load_dwordx4 v[246:249], v[6:7], off offset:1216
	s_waitcnt vmcnt(47)
	v_mfma_f32_16x16x32_bf16 v[34:37], v[250:253], v[226:229], v[34:37]
	global_load_dwordx4 v[250:253], v[14:15], off offset:1216
	v_mfma_f32_16x16x32_bf16 v[38:41], v[242:245], v[226:229], v[38:41]
	global_load_dwordx4 v[226:229], v[8:9], off offset:1216
	global_load_dwordx4 v[242:245], v[10:11], off offset:1216
	s_waitcnt vmcnt(48)
	v_mfma_f32_16x16x32_bf16 v[26:29], v[42:45], v[54:57], v[26:29]
	global_load_dwordx4 v[42:45], v[6:7], off offset:1280
	s_waitcnt vmcnt(48)
	v_mfma_f32_16x16x32_bf16 v[30:33], v[50:53], v[54:57], v[30:33]
	global_load_dwordx4 v[50:53], v[12:13], off offset:1280
	s_waitcnt vmcnt(47)
	v_mfma_f32_16x16x32_bf16 v[34:37], v[62:65], v[54:57], v[34:37]
	global_load_dwordx4 v[62:65], v[8:9], off offset:1280
	s_waitcnt vmcnt(47)
	v_mfma_f32_16x16x32_bf16 v[38:41], v[74:77], v[54:57], v[38:41]
	global_load_dwordx4 v[54:57], v[12:13], off offset:1344
	global_load_dwordx4 v[74:77], v[10:11], off offset:1280
	s_waitcnt vmcnt(48)
	v_mfma_f32_16x16x32_bf16 v[26:29], v[46:49], v[66:69], v[26:29]
	global_load_dwordx4 v[46:49], v[14:15], off offset:1280
	s_waitcnt vmcnt(47)
	v_mfma_f32_16x16x32_bf16 v[30:33], v[78:81], v[66:69], v[30:33]
	global_load_dwordx4 v[78:81], v[6:7], off offset:1344
	s_waitcnt vmcnt(47)
	v_mfma_f32_16x16x32_bf16 v[34:37], v[58:61], v[66:69], v[34:37]
	global_load_dwordx4 v[58:61], v[14:15], off offset:1344
	v_mfma_f32_16x16x32_bf16 v[38:41], v[70:73], v[66:69], v[38:41]
	global_load_dwordx4 v[70:73], v[8:9], off offset:1344
	global_load_dwordx4 v[66:69], v[10:11], off offset:1344
	s_waitcnt vmcnt(48)
	v_mfma_f32_16x16x32_bf16 v[26:29], v[82:85], v[90:93], v[26:29]
	s_waitcnt vmcnt(47)
; #define LAS __attribute__((address_space(3)))
;     ...
;             for (int rb = 0; rb < RB; ++rb) acc[rb] = __builtin_amdgcn_mfma_f32_16x16x32_bf16(a0[rb], b0, acc[rb], 0, 0, 0);
; #pragma unroll
;             for (int rb = 0; rb < RB; ++rb) acc[rb] = __builtin_amdgcn_mfma_f32_16x16x32_bf16(a1[rb], b1, acc[rb], 0, 0, 0);
;             b0 = nb0; b1 = nb1;
; #pragma unroll
;             for (int rb = 0; rb < RB; ++rb) { a0[rb] = na0[rb]; a1[rb] = na1[rb]; }
;         }
; #pragma unroll
;         for (int rb = 0; rb < RB; ++rb)
; #pragma unroll
;             for (int j = 0; j < 4; ++j) red[(wave * (RB * 16) + rb * 16 + 4 * fq + j) * 16 + fr] = acc[rb][j];
;         __syncthreads();
;         if (tid < RB * 64) { const int e = tid * 4, row = e >> 4, col = e & 15;
;             f32x4 v = *(const LAS f32x4*)(red + row * 16 + col);
; #pragma unroll
;             for (int w = 1; w < 8; ++w) v += *(const LAS f32x4*)(red + (w * (RB * 16) + row) * 16 + col);
;             E(rin + row, rh, ct * 16 + col, v); }
;         __syncthreads();
;     }
; }
	v_mfma_f32_16x16x32_bf16 v[30:33], v[98:101], v[90:93], v[30:33]
	s_waitcnt vmcnt(45)
	v_mfma_f32_16x16x32_bf16 v[34:37], v[102:105], v[90:93], v[34:37]
	s_waitcnt vmcnt(44)
	v_mfma_f32_16x16x32_bf16 v[38:41], v[106:109], v[90:93], v[38:41]
	s_waitcnt vmcnt(43)
	v_mfma_f32_16x16x32_bf16 v[26:29], v[114:117], v[86:89], v[26:29]
	s_waitcnt vmcnt(41)
	v_mfma_f32_16x16x32_bf16 v[30:33], v[110:113], v[86:89], v[30:33]
	s_waitcnt vmcnt(40)
	v_mfma_f32_16x16x32_bf16 v[34:37], v[94:97], v[86:89], v[34:37]
	v_mfma_f32_16x16x32_bf16 v[38:41], v[118:121], v[86:89], v[38:41]
	s_waitcnt vmcnt(38)
	v_mfma_f32_16x16x32_bf16 v[26:29], v[122:125], v[130:133], v[26:29]
	s_waitcnt vmcnt(37)
	v_mfma_f32_16x16x32_bf16 v[30:33], v[138:141], v[130:133], v[30:33]
	s_waitcnt vmcnt(35)
	v_mfma_f32_16x16x32_bf16 v[34:37], v[126:129], v[130:133], v[34:37]
	s_waitcnt vmcnt(34)
	v_mfma_f32_16x16x32_bf16 v[38:41], v[146:149], v[130:133], v[38:41]
	s_waitcnt vmcnt(33)
	v_mfma_f32_16x16x32_bf16 v[26:29], v[154:157], v[142:145], v[26:29]
	s_waitcnt vmcnt(31)
	v_mfma_f32_16x16x32_bf16 v[30:33], v[150:153], v[142:145], v[30:33]
	s_waitcnt vmcnt(30)
	v_mfma_f32_16x16x32_bf16 v[34:37], v[134:137], v[142:145], v[34:37]
	v_mfma_f32_16x16x32_bf16 v[38:41], v[158:161], v[142:145], v[38:41]
	s_waitcnt vmcnt(28)
	v_mfma_f32_16x16x32_bf16 v[26:29], v[162:165], v[170:173], v[26:29]
	s_waitcnt vmcnt(27)
	v_mfma_f32_16x16x32_bf16 v[30:33], v[178:181], v[170:173], v[30:33]
	s_waitcnt vmcnt(25)
	v_mfma_f32_16x16x32_bf16 v[34:37], v[166:169], v[170:173], v[34:37]
	s_waitcnt vmcnt(24)
	v_mfma_f32_16x16x32_bf16 v[38:41], v[186:189], v[170:173], v[38:41]
	s_waitcnt vmcnt(23)
	v_mfma_f32_16x16x32_bf16 v[26:29], v[202:205], v[182:185], v[26:29]
	s_waitcnt vmcnt(21)
	v_mfma_f32_16x16x32_bf16 v[30:33], v[174:177], v[182:185], v[30:33]
	s_waitcnt vmcnt(20)
	v_mfma_f32_16x16x32_bf16 v[34:37], v[198:201], v[182:185], v[34:37]
	v_mfma_f32_16x16x32_bf16 v[38:41], v[210:213], v[182:185], v[38:41]
	s_waitcnt vmcnt(18)
	v_mfma_f32_16x16x32_bf16 v[26:29], v[214:217], v[222:225], v[26:29]
	s_waitcnt vmcnt(17)
	v_mfma_f32_16x16x32_bf16 v[30:33], v[230:233], v[222:225], v[30:33]
	s_waitcnt vmcnt(15)
	v_mfma_f32_16x16x32_bf16 v[34:37], v[234:237], v[222:225], v[34:37]
	s_waitcnt vmcnt(14)
	v_mfma_f32_16x16x32_bf16 v[38:41], v[238:241], v[222:225], v[38:41]
	s_waitcnt vmcnt(13)
	v_mfma_f32_16x16x32_bf16 v[26:29], v[246:249], v[218:221], v[26:29]
	s_waitcnt vmcnt(11)
	v_mfma_f32_16x16x32_bf16 v[30:33], v[226:229], v[218:221], v[30:33]
	s_waitcnt vmcnt(10)
	v_mfma_f32_16x16x32_bf16 v[34:37], v[242:245], v[218:221], v[34:37]
	v_mfma_f32_16x16x32_bf16 v[38:41], v[250:253], v[218:221], v[38:41]
	s_waitcnt vmcnt(8)
	v_mfma_f32_16x16x32_bf16 v[26:29], v[42:45], v[50:53], v[26:29]
	s_waitcnt vmcnt(7)
	v_mfma_f32_16x16x32_bf16 v[30:33], v[62:65], v[50:53], v[30:33]
	s_waitcnt vmcnt(5)
	v_mfma_f32_16x16x32_bf16 v[34:37], v[74:77], v[50:53], v[34:37]
	s_waitcnt vmcnt(4)
	v_mfma_f32_16x16x32_bf16 v[38:41], v[46:49], v[50:53], v[38:41]
	s_waitcnt vmcnt(3)
	v_mfma_f32_16x16x32_bf16 v[26:29], v[78:81], v[54:57], v[26:29]
	s_waitcnt vmcnt(1)
	v_mfma_f32_16x16x32_bf16 v[30:33], v[70:73], v[54:57], v[30:33]
	s_waitcnt vmcnt(0)
	v_mfma_f32_16x16x32_bf16 v[34:37], v[66:69], v[54:57], v[34:37]
	v_mfma_f32_16x16x32_bf16 v[38:41], v[58:61], v[54:57], v[38:41]
	s_nop 7
	s_nop 1
	ds_write2_b32 v21, v26, v27 offset1:16
	ds_write2_b32 v21, v28, v29 offset0:32 offset1:48
	ds_write2_b32 v22, v30, v31 offset1:16
	ds_write2_b32 v22, v32, v33 offset0:32 offset1:48
	ds_write2_b32 v23, v34, v35 offset1:16
	ds_write2_b32 v23, v36, v37 offset0:32 offset1:48
	ds_write2_b32 v24, v38, v39 offset1:16
	ds_write2_b32 v24, v40, v41 offset0:32 offset1:48
	s_waitcnt lgkmcnt(0)
	s_barrier
	s_and_saveexec_b64 s[0:1], vcc
	s_cbranch_execz .LBB0_871
	s_lshl_b32 s19, s19, 11
	v_and_or_b32 v0, s20, 64, v208
	v_subrev_u32_e32 v6, s19, v20
	v_lshlrev_b32_e32 v0, 13, v0
	v_ashrrev_i32_e32 v7, 31, v6
	v_lshl_add_u64 v[8:9], s[4:5], 0, v[0:1]
	v_lshlrev_b64 v[14:15], 2, v[6:7]
	v_lshl_add_u64 v[6:7], v[8:9], 0, v[14:15]
	global_load_dwordx4 v[6:9], v[6:7], off
	ds_read_b128 v[10:13], v18
	ds_read_b128 v[26:29], v18 offset:4096
	ds_read_b128 v[30:33], v18 offset:8192
	ds_read_b128 v[34:37], v18 offset:12288
	ds_read_b128 v[38:41], v18 offset:16384
	ds_read_b128 v[42:45], v18 offset:20480
	ds_read_b128 v[46:49], v18 offset:24576
	ds_read_b128 v[50:53], v18 offset:28672
	s_waitcnt lgkmcnt(6)
	v_pk_add_f32 v[12:13], v[12:13], v[28:29]
	v_pk_add_f32 v[10:11], v[10:11], v[26:27]
	s_waitcnt lgkmcnt(5)
	v_pk_add_f32 v[12:13], v[12:13], v[32:33]
	v_pk_add_f32 v[10:11], v[10:11], v[30:31]
	s_waitcnt lgkmcnt(4)
	v_pk_add_f32 v[12:13], v[12:13], v[36:37]
	v_pk_add_f32 v[10:11], v[10:11], v[34:35]
	s_waitcnt lgkmcnt(3)
	v_pk_add_f32 v[12:13], v[12:13], v[40:41]
	v_pk_add_f32 v[10:11], v[10:11], v[38:39]
	s_waitcnt lgkmcnt(2)
	v_pk_add_f32 v[12:13], v[12:13], v[44:45]
	v_pk_add_f32 v[10:11], v[10:11], v[42:43]
	s_waitcnt lgkmcnt(1)
	v_pk_add_f32 v[12:13], v[12:13], v[48:49]
	v_pk_add_f32 v[10:11], v[10:11], v[46:47]
	v_lshl_add_u64 v[54:55], s[6:7], 0, v[0:1]
	s_waitcnt lgkmcnt(0)
	v_pk_add_f32 v[12:13], v[12:13], v[52:53]
	v_pk_add_f32 v[10:11], v[10:11], v[50:51]
	s_waitcnt vmcnt(0)
	v_pk_add_f32 v[8:9], v[12:13], v[8:9]
	v_pk_add_f32 v[6:7], v[10:11], v[6:7]
	v_lshl_add_u64 v[10:11], v[54:55], 0, v[14:15]
	global_store_dwordx4 v[10:11], v[6:9], off
	s_branch .LBB0_871
